# attention loops: all 504 v_pk_mul_f32 split into scalar v_mul_f32 pairs (packed fp32 beside MFMAs is an anti-lever per docs 7.5)
# baseline (speedup 1.0000x reference)
.LBB0_352:
	s_nop 1
	v_and_b32_e32 v33, 64, v191
	v_xor_b32_e32 v32, 32, v191
	v_add_u32_e32 v33, 64, v33
	v_cmp_lt_i32_e32 vcc, v32, v33
	s_lshl_b32 s0, s55, 22
	s_add_u32 s2, s87, s0
	v_cndmask_b32_e32 v32, v191, v32, vcc
	v_lshlrev_b32_e32 v32, 2, v32
	ds_bpermute_b32 v32, v32, v204
	s_addc_u32 s3, s88, 0
	v_lshlrev_b32_e32 v128, 1, v164
	s_waitcnt lgkmcnt(0)
	v_add_f32_e32 v32, v204, v32
	v_div_scale_f32 v33, s[0:1], v32, v32, 1.0
	v_rcp_f32_e32 v34, v33
	s_lshl_b32 s0, s54, 7
	s_add_u32 s0, s2, s0
	s_addc_u32 s1, s3, 0
	v_fma_f32 v35, -v33, v34, 1.0
	v_fmac_f32_e32 v34, v35, v34
	v_div_scale_f32 v35, vcc, 1.0, v32, 1.0
	v_mul_f32_e32 v36, v35, v34
	v_fma_f32 v37, -v33, v36, v35
	v_fmac_f32_e32 v36, v37, v34
	v_fma_f32 v33, -v33, v36, v35
	v_div_fmas_f32 v33, v33, v34, v36
	v_div_fixup_f32 v34, v33, v32, 1.0
	v_mul_f32_e32 v16, v16, v34
	v_mul_f32_e32 v17, v17, v34
	v_mul_f32_e32 v18, v18, v34
	v_mul_f32_e32 v19, v19, v34
	v_mul_f32_e32 v0, v0, v34
	v_mul_f32_e32 v1, v1, v34
	v_mul_f32_e32 v2, v2, v34
	v_mul_f32_e32 v3, v3, v34
	v_lshlrev_b64 v[32:33], 11, v[130:131]
	v_cvt_pk_bf16_f32 v16, v16, v17
	v_cvt_pk_bf16_f32 v17, v18, v19
	v_mul_f32_e32 v18, v20, v34
	v_mul_f32_e32 v19, v21, v34
	v_mul_f32_e32 v20, v22, v34
	v_mul_f32_e32 v21, v23, v34
	v_cvt_pk_bf16_f32 v0, v0, v1
	v_cvt_pk_bf16_f32 v1, v2, v3
	v_mul_f32_e32 v2, v4, v34
	v_mul_f32_e32 v3, v5, v34
	v_mul_f32_e32 v4, v6, v34
	v_mul_f32_e32 v5, v7, v34
	v_lshl_add_u64 v[32:33], s[0:1], 0, v[32:33]
	v_cvt_pk_bf16_f32 v18, v18, v19
	v_cvt_pk_bf16_f32 v19, v20, v21
	v_cvt_pk_bf16_f32 v2, v2, v3
	v_cvt_pk_bf16_f32 v3, v4, v5
	v_lshl_add_u64 v[32:33], v[32:33], 0, v[128:129]
	v_permlane32_swap_b32_e32 v16, v18
	v_permlane32_swap_b32_e32 v17, v19
	v_permlane32_swap_b32_e32 v0, v2
	v_permlane32_swap_b32_e32 v1, v3
	global_store_dwordx4 v[32:33], v[16:19], off
	global_store_dwordx4 v[32:33], v[0:3], off offset:64
	v_mul_f32_e32 v20, v30, v34
	v_mul_f32_e32 v21, v31, v34
	v_mul_f32_e32 v16, v24, v34
	v_mul_f32_e32 v17, v25, v34
	v_mul_f32_e32 v18, v26, v34
	v_mul_f32_e32 v19, v27, v34
	v_mul_f32_e32 v0, v8, v34
	v_mul_f32_e32 v1, v9, v34
	v_mul_f32_e32 v2, v10, v34
	v_mul_f32_e32 v3, v11, v34
	v_cvt_pk_bf16_f32 v16, v16, v17
	v_cvt_pk_bf16_f32 v17, v18, v19
	v_mul_f32_e32 v18, v28, v34
	v_mul_f32_e32 v19, v29, v34
	v_cvt_pk_bf16_f32 v0, v0, v1
	v_cvt_pk_bf16_f32 v1, v2, v3
	v_mul_f32_e32 v2, v12, v34
	v_mul_f32_e32 v3, v13, v34
	v_mul_f32_e32 v4, v14, v34
	v_mul_f32_e32 v5, v15, v34
	v_cvt_pk_bf16_f32 v18, v18, v19
	v_cvt_pk_bf16_f32 v19, v20, v21
	v_cvt_pk_bf16_f32 v2, v2, v3
	v_cvt_pk_bf16_f32 v3, v4, v5
	v_permlane32_swap_b32_e32 v16, v18
	v_permlane32_swap_b32_e32 v17, v19
	v_permlane32_swap_b32_e32 v0, v2
	v_permlane32_swap_b32_e32 v1, v3
	global_store_dwordx4 v[32:33], v[16:19], off offset:32

.LBB0_374:
	s_and_b64 vcc, exec, s[0:1]
	s_cbranch_vccnz .LBB0_380
	v_add_u32_e32 v114, v160, v161
	ds_read_b64_tr_b16 v[126:127], v114 offset:33408
	ds_read_b64_tr_b16 v[120:121], v114 offset:34560
	ds_read_b64_tr_b16 v[112:113], v114 offset:34624
	ds_read_b64_tr_b16 v[118:119], v114 offset:33472
	ds_read_b64_tr_b16 v[124:125], v114 offset:32256
	ds_read_b64_tr_b16 v[122:123], v114 offset:35712
	ds_read_b64_tr_b16 v[116:117], v114 offset:32320
	ds_read_b64_tr_b16 v[114:115], v114 offset:35776
	s_add_i32 s8, s62, 0xffffffa0
	s_mov_b64 s[0:1], -1
	s_cmp_lt_i32 s8, 32
	v_mul_f32_e32 v183, 0x3e38aa3b, v48
	v_mul_f32_e32 v182, 0x3e38aa3b, v49
	v_mul_f32_e32 v181, 0x3e38aa3b, v50
	v_mul_f32_e32 v180, 0x3e38aa3b, v51
	v_mul_f32_e32 v179, 0x3e38aa3b, v52
	v_mul_f32_e32 v178, 0x3e38aa3b, v53
	v_mul_f32_e32 v177, 0x3e38aa3b, v54
	v_mul_f32_e32 v176, 0x3e38aa3b, v55
	v_mul_f32_e32 v175, 0x3e38aa3b, v56
	v_mul_f32_e32 v174, 0x3e38aa3b, v57
	v_mul_f32_e32 v173, 0x3e38aa3b, v58
	v_mul_f32_e32 v172, 0x3e38aa3b, v59
	v_mul_f32_e32 v171, 0x3e38aa3b, v60
	v_mul_f32_e32 v170, 0x3e38aa3b, v61
	v_mul_f32_e32 v169, 0x3e38aa3b, v62
	v_mul_f32_e32 v168, 0x3e38aa3b, v63
	s_cbranch_scc1 .LBB0_377
	v_med3_f32 v142, v175, s49, v190
	v_exp_f32_e32 v148, v142
	v_med3_f32 v142, v174, s49, v190
	v_exp_f32_e32 v149, v142
	v_med3_f32 v143, v173, s49, v190
	v_exp_f32_e32 v150, v143
	v_med3_f32 v143, v172, s49, v190
	v_exp_f32_e32 v151, v143
	v_med3_f32 v143, v171, s49, v190
	v_add_f32_e32 v142, 1.0, v148
	v_exp_f32_e32 v154, v143
	v_med3_f32 v143, v170, s49, v190
	v_med3_f32 v48, v183, s49, v190
	v_med3_f32 v50, v181, s49, v190
	v_med3_f32 v54, v179, s49, v190
	v_med3_f32 v58, v177, s49, v190
	v_rcp_f32_e32 v144, v142
	v_add_f32_e32 v142, 1.0, v149
	v_exp_f32_e32 v155, v143
	v_med3_f32 v143, v169, s49, v190
	v_exp_f32_e32 v52, v48
	v_med3_f32 v48, v182, s49, v190
	v_exp_f32_e32 v56, v50
	v_med3_f32 v50, v180, s49, v190
	v_exp_f32_e32 v60, v54
	v_med3_f32 v54, v178, s49, v190
	v_exp_f32_e32 v62, v58
	v_med3_f32 v58, v176, s49, v190
	v_rcp_f32_e32 v145, v142
	v_add_f32_e32 v142, 1.0, v150
	v_exp_f32_e32 v184, v143
	v_med3_f32 v143, v168, s49, v190
	v_exp_f32_e32 v53, v48
	v_exp_f32_e32 v57, v50
	v_exp_f32_e32 v61, v54
	v_exp_f32_e32 v63, v58
	v_rcp_f32_e32 v146, v142
	v_add_f32_e32 v142, 1.0, v151
	v_exp_f32_e32 v185, v143
	v_rcp_f32_e32 v147, v142
	v_add_f32_e32 v142, 1.0, v154
	v_rcp_f32_e32 v152, v142
	v_add_f32_e32 v142, 1.0, v155
	v_rcp_f32_e32 v153, v142
	v_add_f32_e32 v142, 1.0, v184
	v_add_f32_e32 v48, 1.0, v52
	v_add_f32_e32 v49, 1.0, v53
	v_add_f32_e32 v50, 1.0, v56
	v_add_f32_e32 v51, 1.0, v57
	v_add_f32_e32 v54, 1.0, v60
	v_add_f32_e32 v55, 1.0, v61
	v_add_f32_e32 v58, 1.0, v62
	v_add_f32_e32 v59, 1.0, v63
	v_rcp_f32_e32 v156, v142
	v_add_f32_e32 v142, 1.0, v185
	v_rcp_f32_e32 v48, v48
	v_rcp_f32_e32 v49, v49
	v_rcp_f32_e32 v50, v50
	v_rcp_f32_e32 v51, v51
	v_rcp_f32_e32 v54, v54
	v_rcp_f32_e32 v55, v55
	v_rcp_f32_e32 v58, v58
	v_rcp_f32_e32 v59, v59
	v_rcp_f32_e32 v157, v142
	v_mul_f32_e32 v52, v52, v48
	v_mul_f32_e32 v53, v53, v49
	v_mul_f32_e32 v56, v56, v50
	v_mul_f32_e32 v57, v57, v51
	v_mul_f32_e32 v60, v60, v54
	v_mul_f32_e32 v61, v61, v55
	v_mul_f32_e32 v142, v62, v58
	v_mul_f32_e32 v143, v63, v59
	v_mul_f32_e32 v62, v148, v144
	v_mul_f32_e32 v63, v149, v145
	v_mul_f32_e32 v148, v150, v146
	v_mul_f32_e32 v149, v151, v147
	v_mul_f32_e32 v150, v154, v152
	v_mul_f32_e32 v151, v155, v153
	v_mul_f32_e32 v154, v184, v156
	v_mul_f32_e32 v155, v185, v157
	s_mov_b64 s[0:1], 0

.LBB0_379:
	v_and_b32_e32 v169, 64, v191
	v_xor_b32_e32 v168, 32, v191
	v_add_u32_e32 v169, 64, v169
	v_cmp_lt_i32_e32 vcc, v168, v169
	v_mul_f32_e32 v169, v157, v156
	s_nop 0
	v_cndmask_b32_e32 v168, v191, v168, vcc
	v_lshlrev_b32_e32 v170, 2, v168
	v_mul_f32_e32 v168, v169, v153
	v_mul_f32_e32 v171, v168, v152
	ds_bpermute_b32 v172, v170, v171
	s_waitcnt lgkmcnt(0)
	v_cndmask_b32_e64 v152, 1.0, v172, s[4:5]
	v_mul_f32_e32 v153, v167, v152
	v_mul_f32_e32 v152, v157, v153
	v_mul_f32_e32 v157, v147, v146
	v_mul_f32_e32 v156, v157, v145
	v_mul_f32_e32 v154, v154, v152
	v_mul_f32_e32 v155, v155, v153
	v_mov_b32_e32 v152, v153
	v_mul_f32_e32 v146, v156, v144
	ds_bpermute_b32 v173, v170, v146
	v_mul_f32_e32 v144, v168, v152
	v_mul_f32_e32 v145, v169, v152
	v_mul_f32_e32 v153, v59, v58
	v_mul_f32_e32 v152, v153, v55
	v_mul_f32_e32 v168, v152, v54
	ds_bpermute_b32 v169, v170, v168
	v_mul_f32_e32 v144, v150, v144
	v_mul_f32_e32 v145, v151, v145
	v_mul_f32_e32 v150, v171, v172
	v_mul_f32_e32 v167, v167, v150
	s_waitcnt lgkmcnt(1)
	v_cndmask_b32_e64 v150, 1.0, v173, s[4:5]
	v_mul_f32_e32 v151, v150, v167
	v_mul_f32_e32 v150, v147, v151
	v_mul_f32_e32 v58, v146, v173
	v_mul_f32_e32 v54, v148, v150
	v_mul_f32_e32 v55, v149, v151
	v_mul_f32_e32 v148, v58, v167
	s_waitcnt lgkmcnt(0)
	v_cndmask_b32_e64 v58, 1.0, v169, s[4:5]
	v_mul_f32_e32 v147, v58, v148
	v_mul_f32_e32 v146, v59, v147
	v_mul_f32_e32 v58, v142, v146
	v_mul_f32_e32 v59, v143, v147
	v_mov_b32_e32 v142, v147
	v_mul_f32_e32 v147, v51, v50
	v_mul_f32_e32 v146, v147, v49
	v_mul_f32_e32 v143, v146, v48
	ds_bpermute_b32 v149, v170, v143
	v_mul_f32_e32 v48, v152, v142
	v_mul_f32_e32 v49, v153, v142
	s_nop 0
	v_mul_f32_e32 v60, v60, v48
	v_mul_f32_e32 v61, v61, v49
	v_mul_f32_e32 v48, v168, v169
	v_mul_f32_e32 v142, v48, v148
	s_waitcnt lgkmcnt(0)
	v_cndmask_b32_e64 v48, 1.0, v149, s[4:5]
	v_mul_f32_e32 v49, v48, v142
	v_mul_f32_e32 v48, v51, v49
	v_mul_f32_e32 v50, v56, v48
	v_mul_f32_e32 v51, v57, v49
	v_mov_b32_e32 v48, v49
	v_mul_f32_e32 v49, v147, v48
	v_mul_f32_e32 v48, v146, v48
	s_nop 0
	v_mul_f32_e32 v48, v52, v48
	v_mul_f32_e32 v49, v53, v49
	v_mov_b32_e32 v52, v151
	v_cvt_pk_bf16_f32 v48, v48, v49
	v_cvt_pk_bf16_f32 v49, v50, v51
	v_cvt_pk_bf16_f32 v50, v60, v61
	v_cvt_pk_bf16_f32 v51, v58, v59
	v_mul_f32_e32 v53, v157, v52
	v_mul_f32_e32 v52, v156, v52
	s_nop 0
	v_mfma_f32_32x32x16_bf16 v[16:31], v[124:127], v[48:51], v[16:31]
	v_mul_f32_e64 v52, v62, v52
	v_mul_f32_e64 v53, v63, v53
	v_cvt_pk_bf16_f32 v52, v52, v53
	v_cvt_pk_bf16_f32 v53, v54, v55
	v_cvt_pk_bf16_f32 v54, v144, v145
	v_cvt_pk_bf16_f32 v55, v154, v155
	v_mfma_f32_32x32x16_bf16 v[0:15], v[116:119], v[48:51], v[0:15]
	v_mul_f32_e32 v48, v143, v149
	v_mul_f32_e32 v167, v48, v142
	v_cmp_gt_f32_e32 vcc, s50, v167
	s_cmp_eq_u64 vcc, exec
	s_cselect_b64 s[0:1], -1, 0
	v_cndmask_b32_e64 v48, 0, 1, s[0:1]
	v_mfma_f32_32x32x16_bf16 v[16:31], v[120:123], v[52:55], v[16:31]
	v_readfirstlane_b32 s17, v48
	v_mfma_f32_32x32x16_bf16 v[0:15], v[112:115], v[52:55], v[0:15]

.LBB0_382:
	s_and_b64 vcc, exec, s[6:7]
	s_cbranch_vccnz .LBB0_388
	v_add_u32_e32 v112, v160, v161
	ds_read_b64_tr_b16 v[124:125], v112 offset:27648
	ds_read_b64_tr_b16 v[126:127], v112 offset:28800
	ds_read_b64_tr_b16 v[118:119], v112 offset:28864
	ds_read_b64_tr_b16 v[116:117], v112 offset:27712
	ds_read_b64_tr_b16 v[120:121], v112 offset:29952
	ds_read_b64_tr_b16 v[122:123], v112 offset:31104
	ds_read_b64_tr_b16 v[114:115], v112 offset:31168
	ds_read_b64_tr_b16 v[112:113], v112 offset:30016
	s_sub_i32 s6, s62, 64
	s_mov_b64 s[0:1], -1
	s_cmp_lt_i32 s6, 32
	v_mul_f32_e32 v183, 0x3e38aa3b, v32
	v_mul_f32_e32 v182, 0x3e38aa3b, v33
	v_mul_f32_e32 v181, 0x3e38aa3b, v34
	v_mul_f32_e32 v180, 0x3e38aa3b, v35
	v_mul_f32_e32 v179, 0x3e38aa3b, v36
	v_mul_f32_e32 v178, 0x3e38aa3b, v37
	v_mul_f32_e32 v177, 0x3e38aa3b, v38
	v_mul_f32_e32 v176, 0x3e38aa3b, v39
	v_mul_f32_e32 v175, 0x3e38aa3b, v40
	v_mul_f32_e32 v174, 0x3e38aa3b, v41
	v_mul_f32_e32 v173, 0x3e38aa3b, v42
	v_mul_f32_e32 v172, 0x3e38aa3b, v43
	v_mul_f32_e32 v171, 0x3e38aa3b, v44
	v_mul_f32_e32 v170, 0x3e38aa3b, v45
	v_mul_f32_e32 v169, 0x3e38aa3b, v46
	v_mul_f32_e32 v168, 0x3e38aa3b, v47
	s_cbranch_scc1 .LBB0_385
	v_med3_f32 v142, v175, s49, v190
	v_exp_f32_e32 v148, v142
	v_med3_f32 v142, v174, s49, v190
	v_exp_f32_e32 v149, v142
	v_med3_f32 v143, v173, s49, v190
	v_exp_f32_e32 v150, v143
	v_med3_f32 v143, v172, s49, v190
	v_exp_f32_e32 v151, v143
	v_med3_f32 v143, v171, s49, v190
	v_add_f32_e32 v142, 1.0, v148
	v_exp_f32_e32 v154, v143
	v_med3_f32 v143, v170, s49, v190
	v_med3_f32 v32, v183, s49, v190
	v_med3_f32 v34, v181, s49, v190
	v_med3_f32 v38, v179, s49, v190
	v_med3_f32 v42, v177, s49, v190
	v_rcp_f32_e32 v144, v142
	v_add_f32_e32 v142, 1.0, v149
	v_exp_f32_e32 v155, v143
	v_med3_f32 v143, v169, s49, v190
	v_exp_f32_e32 v36, v32
	v_med3_f32 v32, v182, s49, v190
	v_exp_f32_e32 v40, v34
	v_med3_f32 v34, v180, s49, v190
	v_exp_f32_e32 v44, v38
	v_med3_f32 v38, v178, s49, v190
	v_exp_f32_e32 v46, v42
	v_med3_f32 v42, v176, s49, v190
	v_rcp_f32_e32 v145, v142
	v_add_f32_e32 v142, 1.0, v150
	v_exp_f32_e32 v184, v143
	v_med3_f32 v143, v168, s49, v190
	v_exp_f32_e32 v37, v32
	v_exp_f32_e32 v41, v34
	v_exp_f32_e32 v45, v38
	v_exp_f32_e32 v47, v42
	v_rcp_f32_e32 v146, v142
	v_add_f32_e32 v142, 1.0, v151
	v_exp_f32_e32 v185, v143
	v_rcp_f32_e32 v147, v142
	v_add_f32_e32 v142, 1.0, v154
	v_rcp_f32_e32 v152, v142
	v_add_f32_e32 v142, 1.0, v155
	v_rcp_f32_e32 v153, v142
	v_add_f32_e32 v142, 1.0, v184
	v_add_f32_e32 v32, 1.0, v36
	v_add_f32_e32 v33, 1.0, v37
	v_add_f32_e32 v34, 1.0, v40
	v_add_f32_e32 v35, 1.0, v41
	v_add_f32_e32 v38, 1.0, v44
	v_add_f32_e32 v39, 1.0, v45
	v_add_f32_e32 v42, 1.0, v46
	v_add_f32_e32 v43, 1.0, v47
	v_rcp_f32_e32 v156, v142
	v_add_f32_e32 v142, 1.0, v185
	v_rcp_f32_e32 v32, v32
	v_rcp_f32_e32 v33, v33
	v_rcp_f32_e32 v34, v34
	v_rcp_f32_e32 v35, v35
	v_rcp_f32_e32 v38, v38
	v_rcp_f32_e32 v39, v39
	v_rcp_f32_e32 v42, v42
	v_rcp_f32_e32 v43, v43
	v_rcp_f32_e32 v157, v142
	v_mul_f32_e32 v36, v36, v32
	v_mul_f32_e32 v37, v37, v33
	v_mul_f32_e32 v40, v40, v34
	v_mul_f32_e32 v41, v41, v35
	v_mul_f32_e32 v44, v44, v38
	v_mul_f32_e32 v45, v45, v39
	v_mul_f32_e32 v142, v46, v42
	v_mul_f32_e32 v143, v47, v43
	v_mul_f32_e32 v46, v148, v144
	v_mul_f32_e32 v47, v149, v145
	v_mul_f32_e32 v148, v150, v146
	v_mul_f32_e32 v149, v151, v147
	v_mul_f32_e32 v150, v154, v152
	v_mul_f32_e32 v151, v155, v153
	v_mul_f32_e32 v154, v184, v156
	v_mul_f32_e32 v155, v185, v157
	s_mov_b64 s[0:1], 0

.LBB0_387:
	v_and_b32_e32 v169, 64, v191
	v_xor_b32_e32 v168, 32, v191
	v_add_u32_e32 v169, 64, v169
	v_cmp_lt_i32_e32 vcc, v168, v169
	v_mul_f32_e32 v169, v157, v156
	s_nop 0
	v_cndmask_b32_e32 v168, v191, v168, vcc
	v_lshlrev_b32_e32 v170, 2, v168
	v_mul_f32_e32 v168, v169, v153
	v_mul_f32_e32 v171, v168, v152
	ds_bpermute_b32 v172, v170, v171
	s_waitcnt lgkmcnt(0)
	v_cndmask_b32_e64 v152, 1.0, v172, s[4:5]
	v_mul_f32_e32 v153, v167, v152
	v_mul_f32_e32 v152, v157, v153
	v_mul_f32_e32 v157, v147, v146
	v_mul_f32_e32 v156, v157, v145
	v_mul_f32_e32 v154, v154, v152
	v_mul_f32_e32 v155, v155, v153
	v_mov_b32_e32 v152, v153
	v_mul_f32_e32 v146, v156, v144
	ds_bpermute_b32 v173, v170, v146
	v_mul_f32_e32 v144, v168, v152
	v_mul_f32_e32 v145, v169, v152
	v_mul_f32_e32 v153, v43, v42
	v_mul_f32_e32 v152, v153, v39
	v_mul_f32_e32 v168, v152, v38
	ds_bpermute_b32 v169, v170, v168
	v_mul_f32_e32 v144, v150, v144
	v_mul_f32_e32 v145, v151, v145
	v_mul_f32_e32 v150, v171, v172
	v_mul_f32_e32 v167, v167, v150
	s_waitcnt lgkmcnt(1)
	v_cndmask_b32_e64 v150, 1.0, v173, s[4:5]
	v_mul_f32_e32 v151, v150, v167
	v_mul_f32_e32 v150, v147, v151
	v_mul_f32_e32 v42, v146, v173
	v_mul_f32_e32 v38, v148, v150
	v_mul_f32_e32 v39, v149, v151
	v_mul_f32_e32 v148, v42, v167
	s_waitcnt lgkmcnt(0)
	v_cndmask_b32_e64 v42, 1.0, v169, s[4:5]
	v_mul_f32_e32 v147, v42, v148
	v_mul_f32_e32 v146, v43, v147
	v_mul_f32_e32 v42, v142, v146
	v_mul_f32_e32 v43, v143, v147
	v_mov_b32_e32 v142, v147
	v_mul_f32_e32 v147, v35, v34
	v_mul_f32_e32 v146, v147, v33
	v_mul_f32_e32 v143, v146, v32
	ds_bpermute_b32 v149, v170, v143
	v_mul_f32_e32 v32, v152, v142
	v_mul_f32_e32 v33, v153, v142
	s_nop 0
	v_mul_f32_e32 v44, v44, v32
	v_mul_f32_e32 v45, v45, v33
	v_mul_f32_e32 v32, v168, v169
	v_mul_f32_e32 v142, v32, v148
	s_waitcnt lgkmcnt(0)
	v_cndmask_b32_e64 v32, 1.0, v149, s[4:5]
	v_mul_f32_e32 v33, v32, v142
	v_mul_f32_e32 v32, v35, v33
	v_mul_f32_e32 v34, v40, v32
	v_mul_f32_e32 v35, v41, v33
	v_mov_b32_e32 v32, v33
	v_mul_f32_e32 v33, v147, v32
	v_mul_f32_e32 v32, v146, v32
	s_nop 0
	v_mul_f32_e32 v32, v36, v32
	v_mul_f32_e32 v33, v37, v33
	v_mov_b32_e32 v36, v151
	v_cvt_pk_bf16_f32 v32, v32, v33
	v_cvt_pk_bf16_f32 v33, v34, v35
	v_cvt_pk_bf16_f32 v34, v44, v45
	v_cvt_pk_bf16_f32 v35, v42, v43
	v_mul_f32_e32 v37, v157, v36
	v_mul_f32_e32 v36, v156, v36
	s_nop 0
	v_mfma_f32_32x32x16_bf16 v[16:31], v[124:127], v[32:35], v[16:31]
	v_mul_f32_e64 v36, v46, v36
	v_mul_f32_e64 v37, v47, v37
	v_cvt_pk_bf16_f32 v36, v36, v37
	v_cvt_pk_bf16_f32 v37, v38, v39
	v_cvt_pk_bf16_f32 v38, v144, v145
	v_cvt_pk_bf16_f32 v39, v154, v155
	v_mfma_f32_32x32x16_bf16 v[0:15], v[116:119], v[32:35], v[0:15]
	v_mul_f32_e32 v32, v143, v149
	v_mul_f32_e32 v167, v32, v142
	v_cmp_gt_f32_e32 vcc, s50, v167
	s_cmp_eq_u64 vcc, exec
	s_cselect_b64 s[0:1], -1, 0
	v_cndmask_b32_e64 v32, 0, 1, s[0:1]
	v_mfma_f32_32x32x16_bf16 v[16:31], v[120:123], v[36:39], v[16:31]
	v_readfirstlane_b32 s17, v32
	v_mfma_f32_32x32x16_bf16 v[0:15], v[112:115], v[36:39], v[0:15]

.LBB0_397:
	v_add_u32_e32 v112, v160, v161
	ds_read_b64_tr_b16 v[124:125], v112 offset:23040
	ds_read_b64_tr_b16 v[126:127], v112 offset:24192
	ds_read_b64_tr_b16 v[118:119], v112 offset:24256
	ds_read_b64_tr_b16 v[116:117], v112 offset:23104
	ds_read_b64_tr_b16 v[120:121], v112 offset:25344
	ds_read_b64_tr_b16 v[122:123], v112 offset:26496
	ds_read_b64_tr_b16 v[114:115], v112 offset:26560
	ds_read_b64_tr_b16 v[112:113], v112 offset:25408
	s_sub_i32 s8, s62, 32
	s_mov_b64 s[0:1], -1
	s_cmp_lt_i32 s8, 32
	v_mul_f32_e32 v183, 0x3e38aa3b, v48
	v_mul_f32_e32 v182, 0x3e38aa3b, v49
	v_mul_f32_e32 v181, 0x3e38aa3b, v50
	v_mul_f32_e32 v180, 0x3e38aa3b, v51
	v_mul_f32_e32 v179, 0x3e38aa3b, v52
	v_mul_f32_e32 v178, 0x3e38aa3b, v53
	v_mul_f32_e32 v177, 0x3e38aa3b, v54
	v_mul_f32_e32 v176, 0x3e38aa3b, v55
	v_mul_f32_e32 v175, 0x3e38aa3b, v56
	v_mul_f32_e32 v174, 0x3e38aa3b, v57
	v_mul_f32_e32 v173, 0x3e38aa3b, v58
	v_mul_f32_e32 v172, 0x3e38aa3b, v59
	v_mul_f32_e32 v171, 0x3e38aa3b, v60
	v_mul_f32_e32 v170, 0x3e38aa3b, v61
	v_mul_f32_e32 v169, 0x3e38aa3b, v62
	v_mul_f32_e32 v168, 0x3e38aa3b, v63
	s_cbranch_scc1 .LBB0_399
	v_med3_f32 v142, v175, s49, v190
	v_exp_f32_e32 v148, v142
	v_med3_f32 v142, v174, s49, v190
	v_exp_f32_e32 v149, v142
	v_med3_f32 v143, v173, s49, v190
	v_exp_f32_e32 v150, v143
	v_med3_f32 v143, v172, s49, v190
	v_exp_f32_e32 v151, v143
	v_med3_f32 v143, v171, s49, v190
	v_add_f32_e32 v142, 1.0, v148
	v_exp_f32_e32 v154, v143
	v_med3_f32 v143, v170, s49, v190
	v_med3_f32 v48, v183, s49, v190
	v_med3_f32 v50, v181, s49, v190
	v_med3_f32 v54, v179, s49, v190
	v_med3_f32 v58, v177, s49, v190
	v_rcp_f32_e32 v144, v142
	v_add_f32_e32 v142, 1.0, v149
	v_exp_f32_e32 v155, v143
	v_med3_f32 v143, v169, s49, v190
	v_exp_f32_e32 v52, v48
	v_med3_f32 v48, v182, s49, v190
	v_exp_f32_e32 v56, v50
	v_med3_f32 v50, v180, s49, v190
	v_exp_f32_e32 v60, v54
	v_med3_f32 v54, v178, s49, v190
	v_exp_f32_e32 v62, v58
	v_med3_f32 v58, v176, s49, v190
	v_rcp_f32_e32 v145, v142
	v_add_f32_e32 v142, 1.0, v150
	v_exp_f32_e32 v184, v143
	v_med3_f32 v143, v168, s49, v190
	v_exp_f32_e32 v53, v48
	v_exp_f32_e32 v57, v50
	v_exp_f32_e32 v61, v54
	v_exp_f32_e32 v63, v58
	v_rcp_f32_e32 v146, v142
	v_add_f32_e32 v142, 1.0, v151
	v_exp_f32_e32 v185, v143
	v_rcp_f32_e32 v147, v142
	v_add_f32_e32 v142, 1.0, v154
	v_rcp_f32_e32 v152, v142
	v_add_f32_e32 v142, 1.0, v155
	v_rcp_f32_e32 v153, v142
	v_add_f32_e32 v142, 1.0, v184
	v_add_f32_e32 v48, 1.0, v52
	v_add_f32_e32 v49, 1.0, v53
	v_add_f32_e32 v50, 1.0, v56
	v_add_f32_e32 v51, 1.0, v57
	v_add_f32_e32 v54, 1.0, v60
	v_add_f32_e32 v55, 1.0, v61
	v_add_f32_e32 v58, 1.0, v62
	v_add_f32_e32 v59, 1.0, v63
	v_rcp_f32_e32 v156, v142
	v_add_f32_e32 v142, 1.0, v185
	v_rcp_f32_e32 v48, v48
	v_rcp_f32_e32 v49, v49
	v_rcp_f32_e32 v50, v50
	v_rcp_f32_e32 v51, v51
	v_rcp_f32_e32 v54, v54
	v_rcp_f32_e32 v55, v55
	v_rcp_f32_e32 v58, v58
	v_rcp_f32_e32 v59, v59
	v_rcp_f32_e32 v157, v142
	v_mul_f32_e32 v52, v52, v48
	v_mul_f32_e32 v53, v53, v49
	v_mul_f32_e32 v56, v56, v50
	v_mul_f32_e32 v57, v57, v51
	v_mul_f32_e32 v60, v60, v54
	v_mul_f32_e32 v61, v61, v55
	v_mul_f32_e32 v142, v62, v58
	v_mul_f32_e32 v143, v63, v59
	v_mul_f32_e32 v62, v148, v144
	v_mul_f32_e32 v63, v149, v145
	v_mul_f32_e32 v148, v150, v146
	v_mul_f32_e32 v149, v151, v147
	v_mul_f32_e32 v150, v154, v152
	v_mul_f32_e32 v151, v155, v153
	v_mul_f32_e32 v154, v184, v156
	v_mul_f32_e32 v155, v185, v157
	s_mov_b64 s[0:1], 0

.LBB0_401:
	v_and_b32_e32 v169, 64, v191
	v_xor_b32_e32 v168, 32, v191
	v_add_u32_e32 v169, 64, v169
	v_cmp_lt_i32_e32 vcc, v168, v169
	v_mul_f32_e32 v169, v157, v156
	s_nop 0
	v_cndmask_b32_e32 v168, v191, v168, vcc
	v_lshlrev_b32_e32 v170, 2, v168
	v_mul_f32_e32 v168, v169, v153
	v_mul_f32_e32 v171, v168, v152
	ds_bpermute_b32 v172, v170, v171
	s_waitcnt lgkmcnt(0)
	v_cndmask_b32_e64 v152, 1.0, v172, s[4:5]
	v_mul_f32_e32 v153, v167, v152
	v_mul_f32_e32 v152, v157, v153
	v_mul_f32_e32 v157, v147, v146
	v_mul_f32_e32 v156, v157, v145
	v_mul_f32_e32 v154, v154, v152
	v_mul_f32_e32 v155, v155, v153
	v_mov_b32_e32 v152, v153
	v_mul_f32_e32 v146, v156, v144
	ds_bpermute_b32 v173, v170, v146
	v_mul_f32_e32 v144, v168, v152
	v_mul_f32_e32 v145, v169, v152
	v_mul_f32_e32 v153, v59, v58
	v_mul_f32_e32 v152, v153, v55
	v_mul_f32_e32 v168, v152, v54
	ds_bpermute_b32 v169, v170, v168
	v_mul_f32_e32 v144, v150, v144
	v_mul_f32_e32 v145, v151, v145
	v_mul_f32_e32 v150, v171, v172
	v_mul_f32_e32 v167, v167, v150
	s_waitcnt lgkmcnt(1)
	v_cndmask_b32_e64 v150, 1.0, v173, s[4:5]
	v_mul_f32_e32 v151, v150, v167
	v_mul_f32_e32 v150, v147, v151
	v_mul_f32_e32 v58, v146, v173
	v_mul_f32_e32 v54, v148, v150
	v_mul_f32_e32 v55, v149, v151
	v_mul_f32_e32 v148, v58, v167
	s_waitcnt lgkmcnt(0)
	v_cndmask_b32_e64 v58, 1.0, v169, s[4:5]
	v_mul_f32_e32 v147, v58, v148
	v_mul_f32_e32 v146, v59, v147
	v_mul_f32_e32 v58, v142, v146
	v_mul_f32_e32 v59, v143, v147
	v_mov_b32_e32 v142, v147
	v_mul_f32_e32 v147, v51, v50
	v_mul_f32_e32 v146, v147, v49
	v_mul_f32_e32 v143, v146, v48
	ds_bpermute_b32 v149, v170, v143
	v_mul_f32_e32 v48, v152, v142
	v_mul_f32_e32 v49, v153, v142
	s_nop 0
	v_mul_f32_e32 v60, v60, v48
	v_mul_f32_e32 v61, v61, v49
	v_mul_f32_e32 v48, v168, v169
	v_mul_f32_e32 v142, v48, v148
	s_waitcnt lgkmcnt(0)
	v_cndmask_b32_e64 v48, 1.0, v149, s[4:5]
	v_mul_f32_e32 v49, v48, v142
	v_mul_f32_e32 v48, v51, v49
	v_mul_f32_e32 v50, v56, v48
	v_mul_f32_e32 v51, v57, v49
	v_mov_b32_e32 v48, v49
	v_mul_f32_e32 v49, v147, v48
	v_mul_f32_e32 v48, v146, v48
	s_nop 0
	v_mul_f32_e32 v48, v52, v48
	v_mul_f32_e32 v49, v53, v49
	v_mov_b32_e32 v52, v151
	v_cvt_pk_bf16_f32 v48, v48, v49
	v_cvt_pk_bf16_f32 v49, v50, v51
	v_cvt_pk_bf16_f32 v50, v60, v61
	v_cvt_pk_bf16_f32 v51, v58, v59
	v_mul_f32_e32 v53, v157, v52
	v_mul_f32_e32 v52, v156, v52
	s_nop 0
	v_mfma_f32_32x32x16_bf16 v[16:31], v[124:127], v[48:51], v[16:31]
	v_mul_f32_e64 v52, v62, v52
	v_mul_f32_e64 v53, v63, v53
	v_cvt_pk_bf16_f32 v52, v52, v53
	v_cvt_pk_bf16_f32 v53, v54, v55
	v_cvt_pk_bf16_f32 v54, v144, v145
	v_cvt_pk_bf16_f32 v55, v154, v155
	v_mfma_f32_32x32x16_bf16 v[0:15], v[116:119], v[48:51], v[0:15]
	v_mul_f32_e32 v48, v143, v149
	v_mul_f32_e32 v167, v48, v142
	v_cmp_gt_f32_e32 vcc, s50, v167
	s_cmp_eq_u64 vcc, exec
	s_cselect_b64 s[0:1], -1, 0
	v_cndmask_b32_e64 v48, 0, 1, s[0:1]
	v_mfma_f32_32x32x16_bf16 v[16:31], v[120:123], v[52:55], v[16:31]
	v_readfirstlane_b32 s17, v48
	v_mfma_f32_32x32x16_bf16 v[0:15], v[112:115], v[52:55], v[0:15]
	s_and_b64 vcc, exec, s[6:7]
	s_cbranch_vccnz .LBB0_391
.LBB0_402:
	v_add_u32_e32 v48, v160, v161
	ds_read_b64_tr_b16 v[60:61], v48 offset:18432
	ds_read_b64_tr_b16 v[62:63], v48 offset:19584
	ds_read_b64_tr_b16 v[54:55], v48 offset:19648
	ds_read_b64_tr_b16 v[52:53], v48 offset:18496
	ds_read_b64_tr_b16 v[56:57], v48 offset:20736
	ds_read_b64_tr_b16 v[58:59], v48 offset:21888
	ds_read_b64_tr_b16 v[50:51], v48 offset:21952
	ds_read_b64_tr_b16 v[48:49], v48 offset:20800
	s_mov_b64 s[0:1], -1
	s_cmp_lt_i32 s62, 32
	v_mul_f32_e32 v157, 0x3e38aa3b, v32
	v_mul_f32_e32 v156, 0x3e38aa3b, v33
	v_mul_f32_e32 v155, 0x3e38aa3b, v34
	v_mul_f32_e32 v154, 0x3e38aa3b, v35
	v_mul_f32_e32 v153, 0x3e38aa3b, v36
	v_mul_f32_e32 v152, 0x3e38aa3b, v37
	v_mul_f32_e32 v151, 0x3e38aa3b, v38
	v_mul_f32_e32 v150, 0x3e38aa3b, v39
	v_mul_f32_e32 v149, 0x3e38aa3b, v40
	v_mul_f32_e32 v148, 0x3e38aa3b, v41
	v_mul_f32_e32 v147, 0x3e38aa3b, v42
	v_mul_f32_e32 v146, 0x3e38aa3b, v43
	v_mul_f32_e32 v145, 0x3e38aa3b, v44
	v_mul_f32_e32 v144, 0x3e38aa3b, v45
	v_mul_f32_e32 v143, 0x3e38aa3b, v46
	v_mul_f32_e32 v142, 0x3e38aa3b, v47
	s_cbranch_scc1 .LBB0_404
	v_med3_f32 v112, v149, s49, v190
	v_exp_f32_e32 v118, v112
	v_med3_f32 v112, v148, s49, v190
	v_exp_f32_e32 v119, v112
	v_med3_f32 v113, v147, s49, v190
	v_exp_f32_e32 v120, v113
	v_med3_f32 v113, v146, s49, v190
	v_exp_f32_e32 v121, v113
	v_med3_f32 v113, v145, s49, v190
	v_add_f32_e32 v112, 1.0, v118
	v_exp_f32_e32 v124, v113
	v_med3_f32 v113, v144, s49, v190
	v_med3_f32 v32, v157, s49, v190
	v_med3_f32 v34, v155, s49, v190
	v_med3_f32 v38, v153, s49, v190
	v_med3_f32 v42, v151, s49, v190
	v_rcp_f32_e32 v114, v112
	v_add_f32_e32 v112, 1.0, v119
	v_exp_f32_e32 v125, v113
	v_med3_f32 v113, v143, s49, v190
	v_exp_f32_e32 v36, v32
	v_med3_f32 v32, v156, s49, v190
	v_exp_f32_e32 v40, v34
	v_med3_f32 v34, v154, s49, v190
	v_exp_f32_e32 v44, v38
	v_med3_f32 v38, v152, s49, v190
	v_exp_f32_e32 v46, v42
	v_med3_f32 v42, v150, s49, v190
	v_rcp_f32_e32 v115, v112
	v_add_f32_e32 v112, 1.0, v120
	v_exp_f32_e32 v168, v113
	v_med3_f32 v113, v142, s49, v190
	v_exp_f32_e32 v37, v32
	v_exp_f32_e32 v41, v34
	v_exp_f32_e32 v45, v38
	v_exp_f32_e32 v47, v42
	v_rcp_f32_e32 v116, v112
	v_add_f32_e32 v112, 1.0, v121
	v_exp_f32_e32 v169, v113
	v_rcp_f32_e32 v117, v112
	v_add_f32_e32 v112, 1.0, v124
	v_rcp_f32_e32 v122, v112
	v_add_f32_e32 v112, 1.0, v125
	v_rcp_f32_e32 v123, v112
	v_add_f32_e32 v112, 1.0, v168
	v_add_f32_e32 v32, 1.0, v36
	v_add_f32_e32 v33, 1.0, v37
	v_add_f32_e32 v34, 1.0, v40
	v_add_f32_e32 v35, 1.0, v41
	v_add_f32_e32 v38, 1.0, v44
	v_add_f32_e32 v39, 1.0, v45
	v_add_f32_e32 v42, 1.0, v46
	v_add_f32_e32 v43, 1.0, v47
	v_rcp_f32_e32 v126, v112
	v_add_f32_e32 v112, 1.0, v169
	v_rcp_f32_e32 v32, v32
	v_rcp_f32_e32 v33, v33
	v_rcp_f32_e32 v34, v34
	v_rcp_f32_e32 v35, v35
	v_rcp_f32_e32 v38, v38
	v_rcp_f32_e32 v39, v39
	v_rcp_f32_e32 v42, v42
	v_rcp_f32_e32 v43, v43
	v_rcp_f32_e32 v127, v112
	v_mul_f32_e32 v36, v36, v32
	v_mul_f32_e32 v37, v37, v33
	v_mul_f32_e32 v40, v40, v34
	v_mul_f32_e32 v41, v41, v35
	v_mul_f32_e32 v44, v44, v38
	v_mul_f32_e32 v45, v45, v39
	v_mul_f32_e32 v112, v46, v42
	v_mul_f32_e32 v113, v47, v43
	v_mul_f32_e32 v46, v118, v114
	v_mul_f32_e32 v47, v119, v115
	v_mul_f32_e32 v118, v120, v116
	v_mul_f32_e32 v119, v121, v117
	v_mul_f32_e32 v120, v124, v122
	v_mul_f32_e32 v121, v125, v123
	v_mul_f32_e32 v124, v168, v126
	v_mul_f32_e32 v125, v169, v127
	s_mov_b64 s[0:1], 0

.LBB0_406:
	v_and_b32_e32 v143, 64, v191
	v_xor_b32_e32 v142, 32, v191
	v_add_u32_e32 v143, 64, v143
	v_cmp_lt_i32_e32 vcc, v142, v143
	v_mul_f32_e32 v143, v127, v126
	s_nop 0
	v_cndmask_b32_e32 v142, v191, v142, vcc
	v_lshlrev_b32_e32 v144, 2, v142
	v_mul_f32_e32 v142, v143, v123
	v_mul_f32_e32 v145, v142, v122
	ds_bpermute_b32 v146, v144, v145
	s_waitcnt lgkmcnt(0)
	v_cndmask_b32_e64 v122, 1.0, v146, s[4:5]
	v_mul_f32_e32 v123, v167, v122
	v_mul_f32_e32 v122, v127, v123
	v_mul_f32_e32 v127, v117, v116
	v_mul_f32_e32 v126, v127, v115
	v_mul_f32_e32 v124, v124, v122
	v_mul_f32_e32 v125, v125, v123
	v_mov_b32_e32 v122, v123
	v_mul_f32_e32 v116, v126, v114
	ds_bpermute_b32 v147, v144, v116
	v_mul_f32_e32 v114, v142, v122
	v_mul_f32_e32 v115, v143, v122
	v_mul_f32_e32 v123, v43, v42
	v_mul_f32_e32 v122, v123, v39
	v_mul_f32_e32 v143, v122, v38
	v_mul_f32_e32 v114, v120, v114
	v_mul_f32_e32 v115, v121, v115
	v_mul_f32_e32 v120, v145, v146
	ds_bpermute_b32 v145, v144, v143
	v_mul_f32_e32 v142, v167, v120
	s_waitcnt lgkmcnt(1)
	v_cndmask_b32_e64 v120, 1.0, v147, s[4:5]
	v_mul_f32_e32 v121, v120, v142
	v_mul_f32_e32 v120, v117, v121
	v_mul_f32_e32 v42, v116, v147
	v_mul_f32_e32 v38, v118, v120
	v_mul_f32_e32 v39, v119, v121
	v_mul_f32_e32 v118, v42, v142
	s_waitcnt lgkmcnt(0)
	v_cndmask_b32_e64 v42, 1.0, v145, s[4:5]
	v_mul_f32_e32 v117, v42, v118
	v_mul_f32_e32 v116, v43, v117
	v_mul_f32_e32 v42, v112, v116
	v_mul_f32_e32 v43, v113, v117
	v_mov_b32_e32 v112, v117
	v_mul_f32_e32 v117, v35, v34
	v_mul_f32_e32 v116, v117, v33
	v_mul_f32_e32 v113, v116, v32
	ds_bpermute_b32 v119, v144, v113
	v_mul_f32_e32 v32, v122, v112
	v_mul_f32_e32 v33, v123, v112
	s_nop 0
	v_mul_f32_e32 v44, v44, v32
	v_mul_f32_e32 v45, v45, v33
	v_mul_f32_e32 v32, v143, v145
	v_mul_f32_e32 v112, v32, v118
	s_waitcnt lgkmcnt(0)
	v_cndmask_b32_e64 v32, 1.0, v119, s[4:5]
	v_mul_f32_e32 v33, v32, v112
	v_mul_f32_e32 v32, v35, v33
	v_mul_f32_e32 v34, v40, v32
	v_mul_f32_e32 v35, v41, v33
	v_mov_b32_e32 v32, v33
	v_mul_f32_e32 v33, v117, v32
	v_mul_f32_e32 v32, v116, v32
	s_nop 0
	v_mul_f32_e32 v32, v36, v32
	v_mul_f32_e32 v33, v37, v33
	v_mov_b32_e32 v36, v121
	v_cvt_pk_bf16_f32 v32, v32, v33
	v_cvt_pk_bf16_f32 v33, v34, v35
	v_cvt_pk_bf16_f32 v34, v44, v45
	v_cvt_pk_bf16_f32 v35, v42, v43
	v_mul_f32_e32 v37, v127, v36
	v_mul_f32_e32 v36, v126, v36
	s_nop 0
	v_mfma_f32_32x32x16_bf16 v[16:31], v[60:63], v[32:35], v[16:31]
	v_mul_f32_e64 v36, v46, v36
	v_mul_f32_e64 v37, v47, v37
	v_cvt_pk_bf16_f32 v36, v36, v37
	v_cvt_pk_bf16_f32 v37, v38, v39
	v_cvt_pk_bf16_f32 v38, v114, v115
	v_cvt_pk_bf16_f32 v39, v124, v125
	v_mfma_f32_32x32x16_bf16 v[0:15], v[52:55], v[32:35], v[0:15]
	v_mul_f32_e32 v32, v113, v119
	v_mul_f32_e32 v167, v32, v112
	v_cmp_gt_f32_e32 vcc, s50, v167
	s_cmp_eq_u64 vcc, exec
	s_cselect_b64 s[0:1], -1, 0
	v_cndmask_b32_e64 v32, 0, 1, s[0:1]
	v_mfma_f32_32x32x16_bf16 v[16:31], v[56:59], v[36:39], v[16:31]
	v_readfirstlane_b32 s17, v32
	v_mfma_f32_32x32x16_bf16 v[0:15], v[48:51], v[36:39], v[0:15]
	s_cmp_eq_u32 s60, 0
	s_cbranch_scc0 .LBB0_392

.LBB0_414:
	s_and_b64 vcc, exec, s[0:1]
	v_add_u32_e32 v168, v160, v161
	s_cbranch_vccnz .LBB0_420
	ds_read_b64_tr_b16 v[126:127], v168 offset:33408
	ds_read_b64_tr_b16 v[120:121], v168 offset:34560
	ds_read_b64_tr_b16 v[112:113], v168 offset:34624
	ds_read_b64_tr_b16 v[118:119], v168 offset:33472
	ds_read_b64_tr_b16 v[124:125], v168 offset:32256
	ds_read_b64_tr_b16 v[122:123], v168 offset:35712
	ds_read_b64_tr_b16 v[116:117], v168 offset:32320
	ds_read_b64_tr_b16 v[114:115], v168 offset:35776
	s_add_i32 s8, s62, 32
	s_mov_b64 s[0:1], -1
	s_cmp_lt_i32 s8, 32
	v_mul_f32_e32 v185, 0x3e38aa3b, v48
	v_mul_f32_e32 v184, 0x3e38aa3b, v49
	v_mul_f32_e32 v183, 0x3e38aa3b, v50
	v_mul_f32_e32 v182, 0x3e38aa3b, v51
	v_mul_f32_e32 v181, 0x3e38aa3b, v52
	v_mul_f32_e32 v180, 0x3e38aa3b, v53
	v_mul_f32_e32 v179, 0x3e38aa3b, v54
	v_mul_f32_e32 v178, 0x3e38aa3b, v55
	v_mul_f32_e32 v177, 0x3e38aa3b, v56
	v_mul_f32_e32 v176, 0x3e38aa3b, v57
	v_mul_f32_e32 v175, 0x3e38aa3b, v58
	v_mul_f32_e32 v174, 0x3e38aa3b, v59
	v_mul_f32_e32 v173, 0x3e38aa3b, v60
	v_mul_f32_e32 v172, 0x3e38aa3b, v61
	v_mul_f32_e32 v171, 0x3e38aa3b, v62
	v_mul_f32_e32 v170, 0x3e38aa3b, v63
	s_cbranch_scc1 .LBB0_417
	v_med3_f32 v142, v177, s49, v190
	v_exp_f32_e32 v148, v142
	v_med3_f32 v142, v176, s49, v190
	v_exp_f32_e32 v149, v142
	v_med3_f32 v143, v175, s49, v190
	v_exp_f32_e32 v150, v143
	v_med3_f32 v143, v174, s49, v190
	v_exp_f32_e32 v151, v143
	v_med3_f32 v143, v173, s49, v190
	v_add_f32_e32 v142, 1.0, v148
	v_exp_f32_e32 v154, v143
	v_med3_f32 v143, v172, s49, v190
	v_med3_f32 v48, v185, s49, v190
	v_med3_f32 v50, v183, s49, v190
	v_med3_f32 v54, v181, s49, v190
	v_med3_f32 v58, v179, s49, v190
	v_rcp_f32_e32 v144, v142
	v_add_f32_e32 v142, 1.0, v149
	v_exp_f32_e32 v155, v143
	v_med3_f32 v143, v171, s49, v190
	v_exp_f32_e32 v52, v48
	v_med3_f32 v48, v184, s49, v190
	v_exp_f32_e32 v56, v50
	v_med3_f32 v50, v182, s49, v190
	v_exp_f32_e32 v60, v54
	v_med3_f32 v54, v180, s49, v190
	v_exp_f32_e32 v62, v58
	v_med3_f32 v58, v178, s49, v190
	v_rcp_f32_e32 v145, v142
	v_add_f32_e32 v142, 1.0, v150
	v_exp_f32_e32 v186, v143
	v_med3_f32 v143, v170, s49, v190
	v_exp_f32_e32 v53, v48
	v_exp_f32_e32 v57, v50
	v_exp_f32_e32 v61, v54
	v_exp_f32_e32 v63, v58
	v_rcp_f32_e32 v146, v142
	v_add_f32_e32 v142, 1.0, v151
	v_exp_f32_e32 v187, v143
	v_rcp_f32_e32 v147, v142
	v_add_f32_e32 v142, 1.0, v154
	v_rcp_f32_e32 v152, v142
	v_add_f32_e32 v142, 1.0, v155
	v_rcp_f32_e32 v153, v142
	v_add_f32_e32 v142, 1.0, v186
	v_add_f32_e32 v48, 1.0, v52
	v_add_f32_e32 v49, 1.0, v53
	v_add_f32_e32 v50, 1.0, v56
	v_add_f32_e32 v51, 1.0, v57
	v_add_f32_e32 v54, 1.0, v60
	v_add_f32_e32 v55, 1.0, v61
	v_add_f32_e32 v58, 1.0, v62
	v_add_f32_e32 v59, 1.0, v63
	v_rcp_f32_e32 v156, v142
	v_add_f32_e32 v142, 1.0, v187
	v_rcp_f32_e32 v48, v48
	v_rcp_f32_e32 v49, v49
	v_rcp_f32_e32 v50, v50
	v_rcp_f32_e32 v51, v51
	v_rcp_f32_e32 v54, v54
	v_rcp_f32_e32 v55, v55
	v_rcp_f32_e32 v58, v58
	v_rcp_f32_e32 v59, v59
	v_rcp_f32_e32 v157, v142
	v_mul_f32_e32 v52, v52, v48
	v_mul_f32_e32 v53, v53, v49
	v_mul_f32_e32 v56, v56, v50
	v_mul_f32_e32 v57, v57, v51
	v_mul_f32_e32 v60, v60, v54
	v_mul_f32_e32 v61, v61, v55
	v_mul_f32_e32 v142, v62, v58
	v_mul_f32_e32 v143, v63, v59
	v_mul_f32_e32 v62, v148, v144
	v_mul_f32_e32 v63, v149, v145
	v_mul_f32_e32 v148, v150, v146
	v_mul_f32_e32 v149, v151, v147
	v_mul_f32_e32 v150, v154, v152
	v_mul_f32_e32 v151, v155, v153
	v_mul_f32_e32 v154, v186, v156
	v_mul_f32_e32 v155, v187, v157
	s_mov_b64 s[0:1], 0

.LBB0_419:
	v_and_b32_e32 v171, 64, v191
	v_xor_b32_e32 v170, 32, v191
	v_add_u32_e32 v171, 64, v171
	v_cmp_lt_i32_e32 vcc, v170, v171
	v_mul_f32_e32 v171, v157, v156
	s_nop 0
	v_cndmask_b32_e32 v170, v191, v170, vcc
	v_lshlrev_b32_e32 v172, 2, v170
	v_mul_f32_e32 v170, v171, v153
	v_mul_f32_e32 v173, v170, v152
	ds_bpermute_b32 v174, v172, v173
	s_waitcnt lgkmcnt(0)
	v_cndmask_b32_e64 v152, 1.0, v174, s[4:5]
	v_mul_f32_e32 v153, v167, v152
	v_mul_f32_e32 v152, v157, v153
	v_mul_f32_e32 v157, v147, v146
	v_mul_f32_e32 v156, v157, v145
	v_mul_f32_e32 v154, v154, v152
	v_mul_f32_e32 v155, v155, v153
	v_mov_b32_e32 v152, v153
	v_mul_f32_e32 v146, v156, v144
	ds_bpermute_b32 v175, v172, v146
	v_mul_f32_e32 v144, v170, v152
	v_mul_f32_e32 v145, v171, v152
	v_mul_f32_e32 v153, v59, v58
	v_mul_f32_e32 v152, v153, v55
	v_mul_f32_e32 v170, v152, v54
	ds_bpermute_b32 v171, v172, v170
	v_mul_f32_e32 v144, v150, v144
	v_mul_f32_e32 v145, v151, v145
	v_mul_f32_e32 v150, v173, v174
	v_mul_f32_e32 v167, v167, v150
	s_waitcnt lgkmcnt(1)
	v_cndmask_b32_e64 v150, 1.0, v175, s[4:5]
	v_mul_f32_e32 v151, v150, v167
	v_mul_f32_e32 v150, v147, v151
	v_mul_f32_e32 v58, v146, v175
	v_mul_f32_e32 v54, v148, v150
	v_mul_f32_e32 v55, v149, v151
	v_mul_f32_e32 v148, v58, v167
	s_waitcnt lgkmcnt(0)
	v_cndmask_b32_e64 v58, 1.0, v171, s[4:5]
	v_mul_f32_e32 v147, v58, v148
	v_mul_f32_e32 v146, v59, v147
	v_mul_f32_e32 v58, v142, v146
	v_mul_f32_e32 v59, v143, v147
	v_mov_b32_e32 v142, v147
	v_mul_f32_e32 v147, v51, v50
	v_mul_f32_e32 v146, v147, v49
	v_mul_f32_e32 v143, v146, v48
	ds_bpermute_b32 v149, v172, v143
	v_mul_f32_e32 v48, v152, v142
	v_mul_f32_e32 v49, v153, v142
	s_nop 0
	v_mul_f32_e32 v60, v60, v48
	v_mul_f32_e32 v61, v61, v49
	v_mul_f32_e32 v48, v170, v171
	v_mul_f32_e32 v142, v48, v148
	s_waitcnt lgkmcnt(0)
	v_cndmask_b32_e64 v48, 1.0, v149, s[4:5]
	v_mul_f32_e32 v49, v48, v142
	v_mul_f32_e32 v48, v51, v49
	v_mul_f32_e32 v50, v56, v48
	v_mul_f32_e32 v51, v57, v49
	v_mov_b32_e32 v48, v49
	v_mul_f32_e32 v49, v147, v48
	v_mul_f32_e32 v48, v146, v48
	s_nop 0
	v_mul_f32_e32 v48, v52, v48
	v_mul_f32_e32 v49, v53, v49
	v_mov_b32_e32 v52, v151
	v_cvt_pk_bf16_f32 v48, v48, v49
	v_cvt_pk_bf16_f32 v49, v50, v51
	v_cvt_pk_bf16_f32 v50, v60, v61
	v_cvt_pk_bf16_f32 v51, v58, v59
	v_mul_f32_e32 v53, v157, v52
	v_mul_f32_e32 v52, v156, v52
	s_nop 0
	v_mfma_f32_32x32x16_bf16 v[16:31], v[124:127], v[48:51], v[16:31]
	v_mul_f32_e64 v52, v62, v52
	v_mul_f32_e64 v53, v63, v53
	v_cvt_pk_bf16_f32 v52, v52, v53
	v_cvt_pk_bf16_f32 v53, v54, v55
	v_cvt_pk_bf16_f32 v54, v144, v145
	v_cvt_pk_bf16_f32 v55, v154, v155
	v_mfma_f32_32x32x16_bf16 v[0:15], v[116:119], v[48:51], v[0:15]
	v_mul_f32_e32 v48, v143, v149
	v_mul_f32_e32 v167, v48, v142
	v_cmp_gt_f32_e32 vcc, s50, v167
	s_cmp_eq_u64 vcc, exec
	s_cselect_b64 s[0:1], -1, 0
	v_cndmask_b32_e64 v48, 0, 1, s[0:1]
	v_mfma_f32_32x32x16_bf16 v[16:31], v[120:123], v[52:55], v[16:31]
	v_readfirstlane_b32 s17, v48
	v_mfma_f32_32x32x16_bf16 v[0:15], v[112:115], v[52:55], v[0:15]

.LBB0_422:
	s_and_b64 vcc, exec, s[6:7]
	s_cbranch_vccnz .LBB0_428
	ds_read_b64_tr_b16 v[124:125], v168 offset:27648
	ds_read_b64_tr_b16 v[126:127], v168 offset:28800
	ds_read_b64_tr_b16 v[118:119], v168 offset:28864
	ds_read_b64_tr_b16 v[116:117], v168 offset:27712
	ds_read_b64_tr_b16 v[120:121], v168 offset:29952
	ds_read_b64_tr_b16 v[122:123], v168 offset:31104
	ds_read_b64_tr_b16 v[114:115], v168 offset:31168
	ds_read_b64_tr_b16 v[112:113], v168 offset:30016
	s_add_i32 s6, s62, 64
	s_mov_b64 s[0:1], -1
	s_cmp_lt_i32 s6, 32
	v_mul_f32_e32 v185, 0x3e38aa3b, v32
	v_mul_f32_e32 v184, 0x3e38aa3b, v33
	v_mul_f32_e32 v183, 0x3e38aa3b, v34
	v_mul_f32_e32 v182, 0x3e38aa3b, v35
	v_mul_f32_e32 v181, 0x3e38aa3b, v36
	v_mul_f32_e32 v180, 0x3e38aa3b, v37
	v_mul_f32_e32 v179, 0x3e38aa3b, v38
	v_mul_f32_e32 v178, 0x3e38aa3b, v39
	v_mul_f32_e32 v177, 0x3e38aa3b, v40
	v_mul_f32_e32 v176, 0x3e38aa3b, v41
	v_mul_f32_e32 v175, 0x3e38aa3b, v42
	v_mul_f32_e32 v174, 0x3e38aa3b, v43
	v_mul_f32_e32 v173, 0x3e38aa3b, v44
	v_mul_f32_e32 v172, 0x3e38aa3b, v45
	v_mul_f32_e32 v171, 0x3e38aa3b, v46
	v_mul_f32_e32 v170, 0x3e38aa3b, v47
	s_cbranch_scc1 .LBB0_425
	v_med3_f32 v142, v177, s49, v190
	v_exp_f32_e32 v148, v142
	v_med3_f32 v142, v176, s49, v190
	v_exp_f32_e32 v149, v142
	v_med3_f32 v143, v175, s49, v190
	v_exp_f32_e32 v150, v143
	v_med3_f32 v143, v174, s49, v190
	v_exp_f32_e32 v151, v143
	v_med3_f32 v143, v173, s49, v190
	v_add_f32_e32 v142, 1.0, v148
	v_exp_f32_e32 v154, v143
	v_med3_f32 v143, v172, s49, v190
	v_med3_f32 v32, v185, s49, v190
	v_med3_f32 v34, v183, s49, v190
	v_med3_f32 v38, v181, s49, v190
	v_med3_f32 v42, v179, s49, v190
	v_rcp_f32_e32 v144, v142
	v_add_f32_e32 v142, 1.0, v149
	v_exp_f32_e32 v155, v143
	v_med3_f32 v143, v171, s49, v190
	v_exp_f32_e32 v36, v32
	v_med3_f32 v32, v184, s49, v190
	v_exp_f32_e32 v40, v34
	v_med3_f32 v34, v182, s49, v190
	v_exp_f32_e32 v44, v38
	v_med3_f32 v38, v180, s49, v190
	v_exp_f32_e32 v46, v42
	v_med3_f32 v42, v178, s49, v190
	v_rcp_f32_e32 v145, v142
	v_add_f32_e32 v142, 1.0, v150
	v_exp_f32_e32 v186, v143
	v_med3_f32 v143, v170, s49, v190
	v_exp_f32_e32 v37, v32
	v_exp_f32_e32 v41, v34
	v_exp_f32_e32 v45, v38
	v_exp_f32_e32 v47, v42
	v_rcp_f32_e32 v146, v142
	v_add_f32_e32 v142, 1.0, v151
	v_exp_f32_e32 v187, v143
	v_rcp_f32_e32 v147, v142
	v_add_f32_e32 v142, 1.0, v154
	v_rcp_f32_e32 v152, v142
	v_add_f32_e32 v142, 1.0, v155
	v_rcp_f32_e32 v153, v142
	v_add_f32_e32 v142, 1.0, v186
	v_add_f32_e32 v32, 1.0, v36
	v_add_f32_e32 v33, 1.0, v37
	v_add_f32_e32 v34, 1.0, v40
	v_add_f32_e32 v35, 1.0, v41
	v_add_f32_e32 v38, 1.0, v44
	v_add_f32_e32 v39, 1.0, v45
	v_add_f32_e32 v42, 1.0, v46
	v_add_f32_e32 v43, 1.0, v47
	v_rcp_f32_e32 v156, v142
	v_add_f32_e32 v142, 1.0, v187
	v_rcp_f32_e32 v32, v32
	v_rcp_f32_e32 v33, v33
	v_rcp_f32_e32 v34, v34
	v_rcp_f32_e32 v35, v35
	v_rcp_f32_e32 v38, v38
	v_rcp_f32_e32 v39, v39
	v_rcp_f32_e32 v42, v42
	v_rcp_f32_e32 v43, v43
	v_rcp_f32_e32 v157, v142
	v_mul_f32_e32 v36, v36, v32
	v_mul_f32_e32 v37, v37, v33
	v_mul_f32_e32 v40, v40, v34
	v_mul_f32_e32 v41, v41, v35
	v_mul_f32_e32 v44, v44, v38
	v_mul_f32_e32 v45, v45, v39
	v_mul_f32_e32 v142, v46, v42
	v_mul_f32_e32 v143, v47, v43
	v_mul_f32_e32 v46, v148, v144
	v_mul_f32_e32 v47, v149, v145
	v_mul_f32_e32 v148, v150, v146
	v_mul_f32_e32 v149, v151, v147
	v_mul_f32_e32 v150, v154, v152
	v_mul_f32_e32 v151, v155, v153
	v_mul_f32_e32 v154, v186, v156
	v_mul_f32_e32 v155, v187, v157
	s_mov_b64 s[0:1], 0

.LBB0_427:
	v_and_b32_e32 v171, 64, v191
	v_xor_b32_e32 v170, 32, v191
	v_add_u32_e32 v171, 64, v171
	v_cmp_lt_i32_e32 vcc, v170, v171
	v_mul_f32_e32 v171, v157, v156
	s_nop 0
	v_cndmask_b32_e32 v170, v191, v170, vcc
	v_lshlrev_b32_e32 v172, 2, v170
	v_mul_f32_e32 v170, v171, v153
	v_mul_f32_e32 v173, v170, v152
	ds_bpermute_b32 v174, v172, v173
	s_waitcnt lgkmcnt(0)
	v_cndmask_b32_e64 v152, 1.0, v174, s[4:5]
	v_mul_f32_e32 v153, v167, v152
	v_mul_f32_e32 v152, v157, v153
	v_mul_f32_e32 v157, v147, v146
	v_mul_f32_e32 v156, v157, v145
	v_mul_f32_e32 v154, v154, v152
	v_mul_f32_e32 v155, v155, v153
	v_mov_b32_e32 v152, v153
	v_mul_f32_e32 v146, v156, v144
	ds_bpermute_b32 v175, v172, v146
	v_mul_f32_e32 v144, v170, v152
	v_mul_f32_e32 v145, v171, v152
	v_mul_f32_e32 v153, v43, v42
	v_mul_f32_e32 v152, v153, v39
	v_mul_f32_e32 v170, v152, v38
	ds_bpermute_b32 v171, v172, v170
	v_mul_f32_e32 v144, v150, v144
	v_mul_f32_e32 v145, v151, v145
	v_mul_f32_e32 v150, v173, v174
	v_mul_f32_e32 v167, v167, v150
	s_waitcnt lgkmcnt(1)
	v_cndmask_b32_e64 v150, 1.0, v175, s[4:5]
	v_mul_f32_e32 v151, v150, v167
	v_mul_f32_e32 v150, v147, v151
	v_mul_f32_e32 v42, v146, v175
	v_mul_f32_e32 v38, v148, v150
	v_mul_f32_e32 v39, v149, v151
	v_mul_f32_e32 v148, v42, v167
	s_waitcnt lgkmcnt(0)
	v_cndmask_b32_e64 v42, 1.0, v171, s[4:5]
	v_mul_f32_e32 v147, v42, v148
	v_mul_f32_e32 v146, v43, v147
	v_mul_f32_e32 v42, v142, v146
	v_mul_f32_e32 v43, v143, v147
	v_mov_b32_e32 v142, v147
	v_mul_f32_e32 v147, v35, v34
	v_mul_f32_e32 v146, v147, v33
	v_mul_f32_e32 v143, v146, v32
	ds_bpermute_b32 v149, v172, v143
	v_mul_f32_e32 v32, v152, v142
	v_mul_f32_e32 v33, v153, v142
	s_nop 0
	v_mul_f32_e32 v44, v44, v32
	v_mul_f32_e32 v45, v45, v33
	v_mul_f32_e32 v32, v170, v171
	v_mul_f32_e32 v142, v32, v148
	s_waitcnt lgkmcnt(0)
	v_cndmask_b32_e64 v32, 1.0, v149, s[4:5]
	v_mul_f32_e32 v33, v32, v142
	v_mul_f32_e32 v32, v35, v33
	v_mul_f32_e32 v34, v40, v32
	v_mul_f32_e32 v35, v41, v33
	v_mov_b32_e32 v32, v33
	v_mul_f32_e32 v33, v147, v32
	v_mul_f32_e32 v32, v146, v32
	s_nop 0
	v_mul_f32_e32 v32, v36, v32
	v_mul_f32_e32 v33, v37, v33
	v_mov_b32_e32 v36, v151
	v_cvt_pk_bf16_f32 v32, v32, v33
	v_cvt_pk_bf16_f32 v33, v34, v35
	v_cvt_pk_bf16_f32 v34, v44, v45
	v_cvt_pk_bf16_f32 v35, v42, v43
	v_mul_f32_e32 v37, v157, v36
	v_mul_f32_e32 v36, v156, v36
	s_nop 0
	v_mfma_f32_32x32x16_bf16 v[16:31], v[124:127], v[32:35], v[16:31]
	v_mul_f32_e64 v36, v46, v36
	v_mul_f32_e64 v37, v47, v37
	v_cvt_pk_bf16_f32 v36, v36, v37
	v_cvt_pk_bf16_f32 v37, v38, v39
	v_cvt_pk_bf16_f32 v38, v144, v145
	v_cvt_pk_bf16_f32 v39, v154, v155
	v_mfma_f32_32x32x16_bf16 v[0:15], v[116:119], v[32:35], v[0:15]
	v_mul_f32_e32 v32, v143, v149
	v_mul_f32_e32 v167, v32, v142
	v_cmp_gt_f32_e32 vcc, s50, v167
	s_cmp_eq_u64 vcc, exec
	s_cselect_b64 s[0:1], -1, 0
	v_cndmask_b32_e64 v32, 0, 1, s[0:1]
	v_mfma_f32_32x32x16_bf16 v[16:31], v[120:123], v[36:39], v[16:31]
	v_readfirstlane_b32 s17, v32
	v_mfma_f32_32x32x16_bf16 v[0:15], v[112:115], v[36:39], v[0:15]

.LBB0_432:
	ds_read_b64_tr_b16 v[124:125], v168 offset:23040
	ds_read_b64_tr_b16 v[126:127], v168 offset:24192
	ds_read_b64_tr_b16 v[118:119], v168 offset:24256
	ds_read_b64_tr_b16 v[116:117], v168 offset:23104
	ds_read_b64_tr_b16 v[120:121], v168 offset:25344
	ds_read_b64_tr_b16 v[122:123], v168 offset:26496
	ds_read_b64_tr_b16 v[114:115], v168 offset:26560
	ds_read_b64_tr_b16 v[112:113], v168 offset:25408
	s_add_i32 s8, s62, 0x60
	s_mov_b64 s[0:1], -1
	s_cmp_lt_i32 s8, 32
	v_mul_f32_e32 v184, 0x3e38aa3b, v48
	v_mul_f32_e32 v183, 0x3e38aa3b, v49
	v_mul_f32_e32 v182, 0x3e38aa3b, v50
	v_mul_f32_e32 v181, 0x3e38aa3b, v51
	v_mul_f32_e32 v180, 0x3e38aa3b, v52
	v_mul_f32_e32 v179, 0x3e38aa3b, v53
	v_mul_f32_e32 v178, 0x3e38aa3b, v54
	v_mul_f32_e32 v177, 0x3e38aa3b, v55
	v_mul_f32_e32 v176, 0x3e38aa3b, v56
	v_mul_f32_e32 v175, 0x3e38aa3b, v57
	v_mul_f32_e32 v174, 0x3e38aa3b, v58
	v_mul_f32_e32 v173, 0x3e38aa3b, v59
	v_mul_f32_e32 v172, 0x3e38aa3b, v60
	v_mul_f32_e32 v171, 0x3e38aa3b, v61
	v_mul_f32_e32 v170, 0x3e38aa3b, v62
	v_mul_f32_e32 v169, 0x3e38aa3b, v63
	s_cbranch_scc1 .LBB0_434
	v_med3_f32 v142, v176, s49, v190
	v_exp_f32_e32 v148, v142
	v_med3_f32 v142, v175, s49, v190
	v_exp_f32_e32 v149, v142
	v_med3_f32 v143, v174, s49, v190
	v_exp_f32_e32 v150, v143
	v_med3_f32 v143, v173, s49, v190
	v_exp_f32_e32 v151, v143
	v_med3_f32 v143, v172, s49, v190
	v_add_f32_e32 v142, 1.0, v148
	v_exp_f32_e32 v154, v143
	v_med3_f32 v143, v171, s49, v190
	v_med3_f32 v48, v184, s49, v190
	v_med3_f32 v50, v182, s49, v190
	v_med3_f32 v54, v180, s49, v190
	v_med3_f32 v58, v178, s49, v190
	v_rcp_f32_e32 v144, v142
	v_add_f32_e32 v142, 1.0, v149
	v_exp_f32_e32 v155, v143
	v_med3_f32 v143, v170, s49, v190
	v_exp_f32_e32 v52, v48
	v_med3_f32 v48, v183, s49, v190
	v_exp_f32_e32 v56, v50
	v_med3_f32 v50, v181, s49, v190
	v_exp_f32_e32 v60, v54
	v_med3_f32 v54, v179, s49, v190
	v_exp_f32_e32 v62, v58
	v_med3_f32 v58, v177, s49, v190
	v_rcp_f32_e32 v145, v142
	v_add_f32_e32 v142, 1.0, v150
	v_exp_f32_e32 v186, v143
	v_med3_f32 v143, v169, s49, v190
	v_exp_f32_e32 v53, v48
	v_exp_f32_e32 v57, v50
	v_exp_f32_e32 v61, v54
	v_exp_f32_e32 v63, v58
	v_rcp_f32_e32 v146, v142
	v_add_f32_e32 v142, 1.0, v151
	v_exp_f32_e32 v187, v143
	v_rcp_f32_e32 v147, v142
	v_add_f32_e32 v142, 1.0, v154
	v_rcp_f32_e32 v152, v142
	v_add_f32_e32 v142, 1.0, v155
	v_rcp_f32_e32 v153, v142
	v_add_f32_e32 v142, 1.0, v186
	v_add_f32_e32 v48, 1.0, v52
	v_add_f32_e32 v49, 1.0, v53
	v_add_f32_e32 v50, 1.0, v56
	v_add_f32_e32 v51, 1.0, v57
	v_add_f32_e32 v54, 1.0, v60
	v_add_f32_e32 v55, 1.0, v61
	v_add_f32_e32 v58, 1.0, v62
	v_add_f32_e32 v59, 1.0, v63
	v_rcp_f32_e32 v156, v142
	v_add_f32_e32 v142, 1.0, v187
	v_rcp_f32_e32 v48, v48
	v_rcp_f32_e32 v49, v49
	v_rcp_f32_e32 v50, v50
	v_rcp_f32_e32 v51, v51
	v_rcp_f32_e32 v54, v54
	v_rcp_f32_e32 v55, v55
	v_rcp_f32_e32 v58, v58
	v_rcp_f32_e32 v59, v59
	v_rcp_f32_e32 v157, v142
	v_mul_f32_e32 v52, v52, v48
	v_mul_f32_e32 v53, v53, v49
	v_mul_f32_e32 v56, v56, v50
	v_mul_f32_e32 v57, v57, v51
	v_mul_f32_e32 v60, v60, v54
	v_mul_f32_e32 v61, v61, v55
	v_mul_f32_e32 v142, v62, v58
	v_mul_f32_e32 v143, v63, v59
	v_mul_f32_e32 v62, v148, v144
	v_mul_f32_e32 v63, v149, v145
	v_mul_f32_e32 v148, v150, v146
	v_mul_f32_e32 v149, v151, v147
	v_mul_f32_e32 v150, v154, v152
	v_mul_f32_e32 v151, v155, v153
	v_mul_f32_e32 v154, v186, v156
	v_mul_f32_e32 v155, v187, v157
	s_mov_b64 s[0:1], 0

.LBB0_436:
	v_and_b32_e32 v170, 64, v191
	v_xor_b32_e32 v169, 32, v191
	v_add_u32_e32 v170, 64, v170
	v_cmp_lt_i32_e32 vcc, v169, v170
	v_mul_f32_e32 v171, v157, v156
	v_mul_f32_e32 v170, v171, v153
	v_cndmask_b32_e32 v169, v191, v169, vcc
	v_lshlrev_b32_e32 v169, 2, v169
	v_mul_f32_e32 v172, v170, v152
	ds_bpermute_b32 v173, v169, v172
	s_waitcnt lgkmcnt(0)
	v_cndmask_b32_e64 v152, 1.0, v173, s[4:5]
	v_mul_f32_e32 v153, v167, v152
	v_mul_f32_e32 v152, v157, v153
	v_mul_f32_e32 v157, v147, v146
	v_mul_f32_e32 v156, v157, v145
	v_mul_f32_e32 v154, v154, v152
	v_mul_f32_e32 v155, v155, v153
	v_mov_b32_e32 v152, v153
	v_mul_f32_e32 v146, v156, v144
	ds_bpermute_b32 v174, v169, v146
	v_mul_f32_e32 v144, v170, v152
	v_mul_f32_e32 v145, v171, v152
	v_mul_f32_e32 v153, v59, v58
	v_mul_f32_e32 v152, v153, v55
	v_mul_f32_e32 v170, v152, v54
	ds_bpermute_b32 v171, v169, v170
	v_mul_f32_e32 v144, v150, v144
	v_mul_f32_e32 v145, v151, v145
	v_mul_f32_e32 v150, v172, v173
	v_mul_f32_e32 v167, v167, v150
	s_waitcnt lgkmcnt(1)
	v_cndmask_b32_e64 v150, 1.0, v174, s[4:5]
	v_mul_f32_e32 v151, v150, v167
	v_mul_f32_e32 v150, v147, v151
	v_mul_f32_e32 v58, v146, v174
	v_mul_f32_e32 v54, v148, v150
	v_mul_f32_e32 v55, v149, v151
	v_mul_f32_e32 v148, v58, v167
	s_waitcnt lgkmcnt(0)
	v_cndmask_b32_e64 v58, 1.0, v171, s[4:5]
	v_mul_f32_e32 v147, v58, v148
	v_mul_f32_e32 v146, v59, v147
	v_mul_f32_e32 v58, v142, v146
	v_mul_f32_e32 v59, v143, v147
	v_mov_b32_e32 v142, v147
	v_mul_f32_e32 v147, v51, v50
	v_mul_f32_e32 v146, v147, v49
	v_mul_f32_e32 v143, v146, v48
	ds_bpermute_b32 v149, v169, v143
	v_mul_f32_e32 v48, v152, v142
	v_mul_f32_e32 v49, v153, v142
	s_nop 0
	v_mul_f32_e32 v60, v60, v48
	v_mul_f32_e32 v61, v61, v49
	v_mul_f32_e32 v48, v170, v171
	v_mul_f32_e32 v142, v48, v148
	s_waitcnt lgkmcnt(0)
	v_cndmask_b32_e64 v48, 1.0, v149, s[4:5]
	v_mul_f32_e32 v49, v48, v142
	v_mul_f32_e32 v48, v51, v49
	v_mul_f32_e32 v50, v56, v48
	v_mul_f32_e32 v51, v57, v49
	v_mov_b32_e32 v48, v49
	v_mul_f32_e32 v49, v147, v48
	v_mul_f32_e32 v48, v146, v48
	s_nop 0
	v_mul_f32_e32 v48, v52, v48
	v_mul_f32_e32 v49, v53, v49
	v_mov_b32_e32 v52, v151
	v_cvt_pk_bf16_f32 v48, v48, v49
	v_cvt_pk_bf16_f32 v49, v50, v51
	v_cvt_pk_bf16_f32 v50, v60, v61
	v_cvt_pk_bf16_f32 v51, v58, v59
	v_mul_f32_e32 v53, v157, v52
	v_mul_f32_e32 v52, v156, v52
	s_nop 0
	v_mfma_f32_32x32x16_bf16 v[16:31], v[124:127], v[48:51], v[16:31]
	v_mul_f32_e64 v52, v62, v52
	v_mul_f32_e64 v53, v63, v53
	v_cvt_pk_bf16_f32 v52, v52, v53
	v_cvt_pk_bf16_f32 v53, v54, v55
	v_cvt_pk_bf16_f32 v54, v144, v145
	v_cvt_pk_bf16_f32 v55, v154, v155
	v_mfma_f32_32x32x16_bf16 v[0:15], v[116:119], v[48:51], v[0:15]
	v_mul_f32_e32 v48, v143, v149
	v_mul_f32_e32 v167, v48, v142
	v_cmp_gt_f32_e32 vcc, s50, v167
	s_cmp_eq_u64 vcc, exec
	s_cselect_b64 s[0:1], -1, 0
	v_cndmask_b32_e64 v48, 0, 1, s[0:1]
	v_mfma_f32_32x32x16_bf16 v[16:31], v[120:123], v[52:55], v[16:31]
	v_readfirstlane_b32 s17, v48
	v_mfma_f32_32x32x16_bf16 v[0:15], v[112:115], v[52:55], v[0:15]
	s_and_b64 vcc, exec, s[6:7]
	s_cbranch_vccnz .LBB0_442
.LBB0_437:
	ds_read_b64_tr_b16 v[60:61], v168 offset:18432
	ds_read_b64_tr_b16 v[62:63], v168 offset:19584
	ds_read_b64_tr_b16 v[54:55], v168 offset:19648
	ds_read_b64_tr_b16 v[52:53], v168 offset:18496
	ds_read_b64_tr_b16 v[56:57], v168 offset:20736
	ds_read_b64_tr_b16 v[58:59], v168 offset:21888
	ds_read_b64_tr_b16 v[50:51], v168 offset:21952
	ds_read_b64_tr_b16 v[48:49], v168 offset:20800
	s_add_i32 s6, s62, 0x80
	s_mov_b64 s[0:1], -1
	s_cmp_lt_i32 s6, 32
	v_mul_f32_e32 v157, 0x3e38aa3b, v32
	v_mul_f32_e32 v156, 0x3e38aa3b, v33
	v_mul_f32_e32 v155, 0x3e38aa3b, v34
	v_mul_f32_e32 v154, 0x3e38aa3b, v35
	v_mul_f32_e32 v153, 0x3e38aa3b, v36
	v_mul_f32_e32 v152, 0x3e38aa3b, v37
	v_mul_f32_e32 v151, 0x3e38aa3b, v38
	v_mul_f32_e32 v150, 0x3e38aa3b, v39
	v_mul_f32_e32 v149, 0x3e38aa3b, v40
	v_mul_f32_e32 v148, 0x3e38aa3b, v41
	v_mul_f32_e32 v147, 0x3e38aa3b, v42
	v_mul_f32_e32 v146, 0x3e38aa3b, v43
	v_mul_f32_e32 v145, 0x3e38aa3b, v44
	v_mul_f32_e32 v144, 0x3e38aa3b, v45
	v_mul_f32_e32 v143, 0x3e38aa3b, v46
	v_mul_f32_e32 v142, 0x3e38aa3b, v47
	s_cbranch_scc1 .LBB0_439
	v_med3_f32 v112, v149, s49, v190
	v_exp_f32_e32 v118, v112
	v_med3_f32 v112, v148, s49, v190
	v_exp_f32_e32 v119, v112
	v_med3_f32 v113, v147, s49, v190
	v_exp_f32_e32 v120, v113
	v_med3_f32 v113, v146, s49, v190
	v_exp_f32_e32 v121, v113
	v_med3_f32 v113, v145, s49, v190
	v_add_f32_e32 v112, 1.0, v118
	v_exp_f32_e32 v124, v113
	v_med3_f32 v113, v144, s49, v190
	v_med3_f32 v32, v157, s49, v190
	v_med3_f32 v34, v155, s49, v190
	v_med3_f32 v38, v153, s49, v190
	v_med3_f32 v42, v151, s49, v190
	v_rcp_f32_e32 v114, v112
	v_add_f32_e32 v112, 1.0, v119
	v_exp_f32_e32 v125, v113
	v_med3_f32 v113, v143, s49, v190
	v_exp_f32_e32 v36, v32
	v_med3_f32 v32, v156, s49, v190
	v_exp_f32_e32 v40, v34
	v_med3_f32 v34, v154, s49, v190
	v_exp_f32_e32 v44, v38
	v_med3_f32 v38, v152, s49, v190
	v_exp_f32_e32 v46, v42
	v_med3_f32 v42, v150, s49, v190
	v_rcp_f32_e32 v115, v112
	v_add_f32_e32 v112, 1.0, v120
	v_exp_f32_e32 v168, v113
	v_med3_f32 v113, v142, s49, v190
	v_exp_f32_e32 v37, v32
	v_exp_f32_e32 v41, v34
	v_exp_f32_e32 v45, v38
	v_exp_f32_e32 v47, v42
	v_rcp_f32_e32 v116, v112
	v_add_f32_e32 v112, 1.0, v121
	v_exp_f32_e32 v169, v113
	v_rcp_f32_e32 v117, v112
	v_add_f32_e32 v112, 1.0, v124
	v_rcp_f32_e32 v122, v112
	v_add_f32_e32 v112, 1.0, v125
	v_rcp_f32_e32 v123, v112
	v_add_f32_e32 v112, 1.0, v168
	v_add_f32_e32 v32, 1.0, v36
	v_add_f32_e32 v33, 1.0, v37
	v_add_f32_e32 v34, 1.0, v40
	v_add_f32_e32 v35, 1.0, v41
	v_add_f32_e32 v38, 1.0, v44
	v_add_f32_e32 v39, 1.0, v45
	v_add_f32_e32 v42, 1.0, v46
	v_add_f32_e32 v43, 1.0, v47
	v_rcp_f32_e32 v126, v112
	v_add_f32_e32 v112, 1.0, v169
	v_rcp_f32_e32 v32, v32
	v_rcp_f32_e32 v33, v33
	v_rcp_f32_e32 v34, v34
	v_rcp_f32_e32 v35, v35
	v_rcp_f32_e32 v38, v38
	v_rcp_f32_e32 v39, v39
	v_rcp_f32_e32 v42, v42
	v_rcp_f32_e32 v43, v43
	v_rcp_f32_e32 v127, v112
	v_mul_f32_e32 v36, v36, v32
	v_mul_f32_e32 v37, v37, v33
	v_mul_f32_e32 v40, v40, v34
	v_mul_f32_e32 v41, v41, v35
	v_mul_f32_e32 v44, v44, v38
	v_mul_f32_e32 v45, v45, v39
	v_mul_f32_e32 v112, v46, v42
	v_mul_f32_e32 v113, v47, v43
	v_mul_f32_e32 v46, v118, v114
	v_mul_f32_e32 v47, v119, v115
	v_mul_f32_e32 v118, v120, v116
	v_mul_f32_e32 v119, v121, v117
	v_mul_f32_e32 v120, v124, v122
	v_mul_f32_e32 v121, v125, v123
	v_mul_f32_e32 v124, v168, v126
	v_mul_f32_e32 v125, v169, v127
	s_mov_b64 s[0:1], 0

.LBB0_441:
	v_and_b32_e32 v143, 64, v191
	v_xor_b32_e32 v142, 32, v191
	v_add_u32_e32 v143, 64, v143
	v_cmp_lt_i32_e32 vcc, v142, v143
	v_mul_f32_e32 v143, v127, v126
	s_nop 0
	v_cndmask_b32_e32 v142, v191, v142, vcc
	v_lshlrev_b32_e32 v144, 2, v142
	v_mul_f32_e32 v142, v143, v123
	v_mul_f32_e32 v145, v142, v122
	ds_bpermute_b32 v146, v144, v145
	s_waitcnt lgkmcnt(0)
	v_cndmask_b32_e64 v122, 1.0, v146, s[4:5]
	v_mul_f32_e32 v123, v167, v122
	v_mul_f32_e32 v122, v127, v123
	v_mul_f32_e32 v127, v117, v116
	v_mul_f32_e32 v126, v127, v115
	v_mul_f32_e32 v124, v124, v122
	v_mul_f32_e32 v125, v125, v123
	v_mov_b32_e32 v122, v123
	v_mul_f32_e32 v116, v126, v114
	ds_bpermute_b32 v147, v144, v116
	v_mul_f32_e32 v114, v142, v122
	v_mul_f32_e32 v115, v143, v122
	v_mul_f32_e32 v123, v43, v42
	v_mul_f32_e32 v122, v123, v39
	v_mul_f32_e32 v143, v122, v38
	v_mul_f32_e32 v114, v120, v114
	v_mul_f32_e32 v115, v121, v115
	v_mul_f32_e32 v120, v145, v146
	ds_bpermute_b32 v145, v144, v143
	v_mul_f32_e32 v142, v167, v120
	s_waitcnt lgkmcnt(1)
	v_cndmask_b32_e64 v120, 1.0, v147, s[4:5]
	v_mul_f32_e32 v121, v120, v142
	v_mul_f32_e32 v120, v117, v121
	v_mul_f32_e32 v42, v116, v147
	v_mul_f32_e32 v38, v118, v120
	v_mul_f32_e32 v39, v119, v121
	v_mul_f32_e32 v118, v42, v142
	s_waitcnt lgkmcnt(0)
	v_cndmask_b32_e64 v42, 1.0, v145, s[4:5]
	v_mul_f32_e32 v117, v42, v118
	v_mul_f32_e32 v116, v43, v117
	v_mul_f32_e32 v42, v112, v116
	v_mul_f32_e32 v43, v113, v117
	v_mov_b32_e32 v112, v117
	v_mul_f32_e32 v117, v35, v34
	v_mul_f32_e32 v116, v117, v33
	v_mul_f32_e32 v113, v116, v32
	ds_bpermute_b32 v119, v144, v113
	v_mul_f32_e32 v32, v122, v112
	v_mul_f32_e32 v33, v123, v112
	s_nop 0
	v_mul_f32_e32 v44, v44, v32
	v_mul_f32_e32 v45, v45, v33
	v_mul_f32_e32 v32, v143, v145
	v_mul_f32_e32 v112, v32, v118
	s_waitcnt lgkmcnt(0)
	v_cndmask_b32_e64 v32, 1.0, v119, s[4:5]
	v_mul_f32_e32 v33, v32, v112
	v_mul_f32_e32 v32, v35, v33
	v_mul_f32_e32 v34, v40, v32
	v_mul_f32_e32 v35, v41, v33
	v_mov_b32_e32 v32, v33
	v_mul_f32_e32 v33, v117, v32
	v_mul_f32_e32 v32, v116, v32
	s_nop 0
	v_mul_f32_e32 v32, v36, v32
	v_mul_f32_e32 v33, v37, v33
	v_mov_b32_e32 v36, v121
	v_cvt_pk_bf16_f32 v32, v32, v33
	v_cvt_pk_bf16_f32 v33, v34, v35
	v_cvt_pk_bf16_f32 v34, v44, v45
	v_cvt_pk_bf16_f32 v35, v42, v43
	v_mul_f32_e32 v37, v127, v36
	v_mul_f32_e32 v36, v126, v36
	s_nop 0
	v_mfma_f32_32x32x16_bf16 v[16:31], v[60:63], v[32:35], v[16:31]
	v_mul_f32_e64 v36, v46, v36
	v_mul_f32_e64 v37, v47, v37
	v_cvt_pk_bf16_f32 v36, v36, v37
	v_cvt_pk_bf16_f32 v37, v38, v39
	v_cvt_pk_bf16_f32 v38, v114, v115
	v_cvt_pk_bf16_f32 v39, v124, v125
	v_mfma_f32_32x32x16_bf16 v[0:15], v[52:55], v[32:35], v[0:15]
	v_mul_f32_e32 v32, v113, v119
	v_mul_f32_e32 v167, v32, v112
	v_cmp_gt_f32_e32 vcc, s50, v167
	s_cmp_eq_u64 vcc, exec
	s_cselect_b64 s[0:1], -1, 0
	v_cndmask_b32_e64 v32, 0, 1, s[0:1]
	v_mfma_f32_32x32x16_bf16 v[16:31], v[56:59], v[36:39], v[16:31]
	v_readfirstlane_b32 s17, v32
	v_mfma_f32_32x32x16_bf16 v[0:15], v[48:51], v[36:39], v[0:15]

.LBB0_457:
	v_mul_f32_e32 v30, v30, v128
	v_mul_f32_e32 v31, v31, v128
	v_mul_f32_e32 v28, v28, v128
	v_mul_f32_e32 v29, v29, v128
	v_mul_f32_e32 v26, v26, v128
	v_mul_f32_e32 v27, v27, v128
	v_mul_f32_e32 v24, v24, v128
	v_mul_f32_e32 v25, v25, v128
	v_mul_f32_e32 v22, v22, v128
	v_mul_f32_e32 v23, v23, v128
	v_mul_f32_e32 v20, v20, v128
	v_mul_f32_e32 v21, v21, v128
	v_mul_f32_e32 v18, v18, v128
	v_mul_f32_e32 v19, v19, v128
	v_mul_f32_e32 v16, v16, v128
	v_mul_f32_e32 v17, v17, v128
	v_mul_f32_e32 v14, v14, v128
	v_mul_f32_e32 v15, v15, v128
	v_mul_f32_e32 v12, v12, v128
	v_mul_f32_e32 v13, v13, v128
	v_mul_f32_e32 v10, v10, v128
	v_mul_f32_e32 v11, v11, v128
	v_mul_f32_e32 v8, v8, v128
	v_mul_f32_e32 v9, v9, v128
	v_mul_f32_e32 v6, v6, v128
	v_mul_f32_e32 v7, v7, v128
	v_mul_f32_e32 v4, v4, v128
	v_mul_f32_e32 v5, v5, v128
	v_mul_f32_e32 v2, v2, v128
	v_mul_f32_e32 v3, v3, v128
	v_mul_f32_e32 v0, v0, v128
	v_mul_f32_e32 v1, v1, v128

.LBB0_482:
	v_mul_f32_e32 v30, v30, v126
	v_mul_f32_e32 v31, v31, v126
	v_mul_f32_e32 v28, v28, v126
	v_mul_f32_e32 v29, v29, v126
	v_mul_f32_e32 v26, v26, v126
	v_mul_f32_e32 v27, v27, v126
	v_mul_f32_e32 v24, v24, v126
	v_mul_f32_e32 v25, v25, v126
	v_mul_f32_e32 v22, v22, v126
	v_mul_f32_e32 v23, v23, v126
	v_mul_f32_e32 v20, v20, v126
	v_mul_f32_e32 v21, v21, v126
	v_mul_f32_e32 v18, v18, v126
	v_mul_f32_e32 v19, v19, v126
	v_mul_f32_e32 v16, v16, v126
	v_mul_f32_e32 v17, v17, v126
	v_mul_f32_e32 v14, v14, v126
	v_mul_f32_e32 v15, v15, v126
	v_mul_f32_e32 v12, v12, v126
	v_mul_f32_e32 v13, v13, v126
	v_mul_f32_e32 v10, v10, v126
	v_mul_f32_e32 v11, v11, v126
	v_mul_f32_e32 v8, v8, v126
	v_mul_f32_e32 v9, v9, v126
	v_mul_f32_e32 v6, v6, v126
	v_mul_f32_e32 v7, v7, v126
	v_mul_f32_e32 v4, v4, v126
	v_mul_f32_e32 v5, v5, v126
	v_mul_f32_e32 v2, v2, v126
	v_mul_f32_e32 v3, v3, v126
	v_mul_f32_e32 v0, v0, v126
	v_mul_f32_e32 v1, v1, v126

.LBB0_525:
	s_andn2_b64 vcc, exec, s[42:43]
	s_cbranch_vccnz .LBB0_527
	v_max3_f32 v128, v208, s53, v209
	v_max3_f32 v128, v128, v210, v211
	v_max3_f32 v128, v128, v212, v213
	v_max3_f32 v128, v128, v214, v215
	v_and_b32_e32 v175, 64, v191
	v_max3_f32 v128, v128, v216, v217
	v_xor_b32_e32 v174, 32, v191
	v_add_u32_e32 v175, 64, v175
	v_max3_f32 v128, v128, v218, v219
	v_cmp_lt_i32_e32 vcc, v174, v175
	v_max3_f32 v128, v128, v220, v221
	v_max3_f32 v128, v128, v222, v223
	v_cndmask_b32_e32 v174, v191, v174, vcc
	v_lshlrev_b32_e32 v174, 2, v174
	ds_bpermute_b32 v174, v174, v128
	s_waitcnt lgkmcnt(0)
	v_max3_f32 v206, v205, v128, v174
	v_fma_f32 v174, v48, s48, -v206
	v_fma_f32 v175, v49, s48, -v206
	v_exp_f32_e32 v174, v174
	v_exp_f32_e32 v175, v175
	v_fma_f32 v176, v50, s48, -v206
	v_fma_f32 v177, v51, s48, -v206
	v_exp_f32_e32 v176, v176
	v_exp_f32_e32 v177, v177
	v_mul_f32_e32 v174, v150, v174
	v_mul_f32_e32 v175, v151, v175
	v_fma_f32 v180, v54, s48, -v206
	v_add_f32_e32 v178, 0, v174
	v_add_f32_e32 v178, v175, v178
	v_mul_f32_e32 v176, v154, v176
	v_mul_f32_e32 v177, v155, v177
	v_exp_f32_e32 v181, v180
	v_add_f32_e32 v178, v176, v178
	v_add_f32_e32 v182, v177, v178
	v_fma_f32 v178, v52, s48, -v206
	v_exp_f32_e32 v179, v178
	v_fma_f32 v178, v53, s48, -v206
	v_exp_f32_e32 v178, v178
	v_fma_f32 v180, v55, s48, -v206
	v_exp_f32_e32 v180, v180
	v_sub_f32_e32 v128, v205, v206
	v_mul_f32_e32 v208, v158, v178
	v_mul_f32_e32 v209, v159, v179
	v_exp_f32_e32 v128, v128
	v_add_f32_e32 v178, v209, v182
	v_add_f32_e32 v178, v208, v178
	v_mul_f32_e32 v180, v162, v180
	v_mul_f32_e32 v181, v163, v181
	v_fma_f32 v182, v58, s48, -v206
	v_add_f32_e32 v178, v181, v178
	v_add_f32_e32 v186, v180, v178
	v_fma_f32 v178, v56, s48, -v206
	v_exp_f32_e32 v179, v178
	v_fma_f32 v178, v57, s48, -v206
	v_exp_f32_e32 v178, v178
	v_exp_f32_e32 v183, v182
	v_fma_f32 v182, v59, s48, -v206
	v_exp_f32_e32 v182, v182
	v_mul_f32_e32 v184, v148, v178
	v_mul_f32_e32 v185, v149, v179
	s_nop 0
	v_add_f32_e32 v178, v185, v186
	v_add_f32_e32 v186, v184, v178
	v_mul_f32_e32 v178, v152, v182
	v_mul_f32_e32 v179, v153, v183
	s_nop 0
	v_add_f32_e32 v182, v179, v186
	v_add_f32_e32 v188, v178, v182
	v_fma_f32 v182, v60, s48, -v206
	v_exp_f32_e32 v183, v182
	v_fma_f32 v182, v61, s48, -v206
	v_exp_f32_e32 v182, v182
	v_fma_f32 v186, v62, s48, -v206
	v_exp_f32_e32 v187, v186
	v_fma_f32 v186, v63, s48, -v206
	v_exp_f32_e32 v186, v186
	v_mul_f32_e32 v182, v156, v182
	v_mul_f32_e32 v183, v157, v183
	v_mul_f32_e32 v186, v160, v186
	v_mul_f32_e32 v187, v161, v187
	v_add_f32_e32 v188, v183, v188
	v_add_f32_e32 v188, v182, v188
	v_add_f32_e32 v188, v187, v188
	v_add_f32_e32 v207, v186, v188
	v_mov_b32_e32 v189, v186
	v_mov_b32_e32 v188, v187
	v_mov_b32_e32 v187, v182
	v_mov_b32_e32 v186, v183
	v_mov_b32_e32 v183, v178
	v_mov_b32_e32 v182, v179
	v_mov_b32_e32 v179, v184
	v_mov_b32_e32 v178, v185
	v_mov_b32_e32 v185, v180
	v_mov_b32_e32 v184, v181
	v_mov_b32_e32 v181, v208
	v_mov_b32_e32 v180, v209

.LBB0_528:
	s_andn2_b64 vcc, exec, s[42:43]
	s_cbranch_vccnz .LBB0_530
	v_mul_f32_e32 v128, v134, v48
	v_mul_f32_e32 v176, v134, v52
	v_fmac_f32_e32 v128, v49, v135
	v_fmac_f32_e32 v176, v53, v135
	v_mul_f32_e32 v180, v134, v56
	v_mul_f32_e32 v181, v134, v60
	v_fmac_f32_e32 v128, v50, v136
	v_fmac_f32_e32 v176, v54, v136
	v_fmac_f32_e32 v180, v57, v135
	v_fmac_f32_e32 v181, v61, v135
	v_fmac_f32_e32 v128, v51, v137
	v_fmac_f32_e32 v176, v55, v137
	v_fmac_f32_e32 v180, v58, v136
	v_fmac_f32_e32 v181, v62, v136
	v_mul_f32_e32 v174, 0x3e38aa3b, v128
	v_mul_f32_e32 v175, 0x3e38aa3b, v176
	v_fmac_f32_e32 v180, v59, v137
	v_fmac_f32_e32 v181, v63, v137
	v_max3_f32 v174, v174, s53, v175
	v_mul_f32_e32 v175, 0x3e38aa3b, v180
	v_mul_f32_e32 v177, 0x3e38aa3b, v181
	v_max3_f32 v174, v174, v175, v177
	v_and_b32_e32 v177, 64, v191
	v_xor_b32_e32 v175, 32, v191
	v_add_u32_e32 v177, 64, v177
	v_cmp_lt_i32_e32 vcc, v175, v177
	s_nop 1
	v_cndmask_b32_e32 v175, v191, v175, vcc
	v_lshlrev_b32_e32 v175, 2, v175
	ds_bpermute_b32 v175, v175, v174
	s_waitcnt lgkmcnt(0)
	v_max3_f32 v206, v205, v174, v175
	v_fma_f32 v128, v128, s48, -v206
	v_exp_f32_e32 v175, v128
	v_fma_f32 v128, v176, s48, -v206
	v_exp_f32_e32 v174, v128
	v_fma_f32 v180, v180, s48, -v206
	v_exp_f32_e32 v183, v180
	v_fma_f32 v180, v181, s48, -v206
	v_exp_f32_e32 v182, v180
	v_sub_f32_e32 v128, v205, v206
	v_mul_f32_e32 v178, v146, v174
	v_mul_f32_e32 v179, v147, v175
	v_exp_f32_e32 v128, v128
	v_add_f32_e32 v186, 0, v179
	v_add_f32_e32 v186, v178, v186
	v_mul_f32_e32 v208, v144, v182
	v_mul_f32_e32 v209, v145, v183
	v_mul_f32_e32 v174, v134, v179
	v_mul_f32_e32 v175, v135, v179
	v_add_f32_e32 v207, v209, v186
	v_mul_f32_e32 v176, v136, v179
	v_mul_f32_e32 v177, v137, v179
	v_mul_f32_e32 v180, v134, v178
	v_mul_f32_e32 v181, v135, v178
	v_mul_f32_e32 v184, v136, v178
	v_mul_f32_e32 v185, v137, v178
	v_mul_f32_e32 v178, v134, v209
	v_mul_f32_e32 v179, v135, v209
	v_mul_f32_e32 v182, v136, v209
	v_mul_f32_e32 v183, v137, v209
	v_mul_f32_e32 v186, v134, v208
	v_mul_f32_e32 v187, v135, v208
	v_mul_f32_e32 v188, v136, v208
	v_mul_f32_e32 v189, v137, v208
	v_add_f32_e32 v207, v208, v207

.LBB0_531:
	v_mul_f32_e32 v48, v132, v48
	v_mul_f32_e32 v56, v132, v56
	v_fmac_f32_e32 v48, v49, v133
	v_fmac_f32_e32 v56, v57, v133
	v_fmac_f32_e32 v48, v50, v138
	v_fmac_f32_e32 v56, v58, v138
	v_fmac_f32_e32 v48, v51, v139
	v_fmac_f32_e32 v56, v59, v139
	v_fmac_f32_e32 v48, v52, v140
	v_fmac_f32_e32 v56, v60, v140
	v_fmac_f32_e32 v48, v53, v141
	v_fmac_f32_e32 v56, v61, v141
	v_and_b32_e32 v52, 64, v191
	v_fmac_f32_e32 v48, v54, v142
	v_fmac_f32_e32 v56, v62, v142
	v_xor_b32_e32 v51, 32, v191
	v_add_u32_e32 v52, 64, v52
	v_fmac_f32_e32 v48, v55, v143
	v_fmac_f32_e32 v56, v63, v143
	v_cmp_lt_i32_e32 vcc, v51, v52
	v_fmamk_f32 v48, v48, 0x3e38aa3b, v196
	v_fmamk_f32 v49, v56, 0x3e38aa3b, v196
	v_cndmask_b32_e32 v51, v191, v51, vcc
	v_max_f32_e32 v50, v48, v49
	v_lshlrev_b32_e32 v51, 2, v51
	ds_bpermute_b32 v51, v51, v50
	s_waitcnt lgkmcnt(0)
	v_max3_f32 v206, v205, v50, v51
	v_sub_f32_e32 v48, v48, v206
	v_sub_f32_e32 v49, v49, v206
	v_exp_f32_e32 v48, v48
	v_exp_f32_e32 v50, v49
	v_sub_f32_e32 v49, v205, v206
	v_exp_f32_e32 v128, v49
	v_mul_f32_e32 v174, v132, v48
	v_mul_f32_e32 v175, v133, v48
	v_mul_f32_e32 v178, v132, v50
	v_mul_f32_e32 v179, v133, v50
	v_mul_f32_e32 v176, v138, v48
	v_mul_f32_e32 v177, v139, v48
	v_mul_f32_e32 v182, v138, v50
	v_mul_f32_e32 v183, v139, v50
	v_mul_f32_e32 v180, v140, v48
	v_mul_f32_e32 v181, v141, v48
	v_mul_f32_e32 v186, v140, v50
	v_mul_f32_e32 v187, v141, v50
	v_mul_f32_e32 v184, v142, v48
	v_mul_f32_e32 v185, v143, v48
	v_mul_f32_e32 v188, v142, v50
	v_mul_f32_e32 v189, v143, v50
	v_add_f32_e32 v207, v48, v50
	v_cmp_eq_f32_e32 vcc, 1.0, v128
	s_cmp_eq_u64 vcc, exec
	s_cbranch_scc0 .LBB0_457
	s_branch .LBB0_458

.LBB0_535:
	s_andn2_b64 vcc, exec, s[0:1]
	s_cbranch_vccnz .LBB0_537
	v_max3_f32 v128, v208, s53, v209
	v_max3_f32 v128, v128, v210, v211
	v_max3_f32 v128, v128, v212, v213
	v_max3_f32 v128, v128, v214, v215
	v_and_b32_e32 v175, 64, v191
	v_max3_f32 v128, v128, v216, v217
	v_xor_b32_e32 v174, 32, v191
	v_add_u32_e32 v175, 64, v175
	v_max3_f32 v128, v128, v218, v219
	v_cmp_lt_i32_e32 vcc, v174, v175
	v_max3_f32 v128, v128, v220, v221
	v_max3_f32 v128, v128, v222, v223
	v_cndmask_b32_e32 v174, v191, v174, vcc
	v_lshlrev_b32_e32 v174, 2, v174
	ds_bpermute_b32 v174, v174, v128
	s_waitcnt lgkmcnt(0)
	v_max3_f32 v205, v206, v128, v174
	v_fma_f32 v128, v32, s48, -v205
	v_exp_f32_e32 v174, v128
	v_fma_f32 v128, v33, s48, -v205
	v_exp_f32_e32 v175, v128
	v_fma_f32 v177, v35, s48, -v205
	v_exp_f32_e32 v177, v177
	v_fma_f32 v178, v36, s48, -v205
	v_mul_f32_e32 v174, v150, v174
	v_mul_f32_e32 v175, v151, v175
	v_exp_f32_e32 v179, v178
	v_add_f32_e32 v176, 0, v174
	v_add_f32_e32 v180, v175, v176
	v_fma_f32 v176, v34, s48, -v205
	v_exp_f32_e32 v176, v176
	v_fma_f32 v178, v37, s48, -v205
	v_exp_f32_e32 v178, v178
	v_fma_f32 v182, v40, s48, -v205
	v_mul_f32_e32 v176, v154, v176
	v_mul_f32_e32 v177, v155, v177
	v_exp_f32_e32 v185, v182
	v_add_f32_e32 v180, v176, v180
	v_add_f32_e32 v180, v177, v180
	v_mul_f32_e32 v178, v158, v178
	v_mul_f32_e32 v179, v159, v179
	v_fma_f32 v182, v41, s48, -v205
	v_add_f32_e32 v180, v179, v180
	v_add_f32_e32 v186, v178, v180
	v_fma_f32 v180, v38, s48, -v205
	v_exp_f32_e32 v181, v180
	v_fma_f32 v180, v39, s48, -v205
	v_exp_f32_e32 v180, v180
	v_exp_f32_e32 v184, v182
	v_sub_f32_e32 v128, v206, v205
	v_exp_f32_e32 v128, v128
	v_mul_f32_e32 v182, v162, v180
	v_mul_f32_e32 v183, v163, v181
	s_nop 0
	v_add_f32_e32 v180, v183, v186
	v_add_f32_e32 v186, v182, v180
	v_mul_f32_e32 v180, v148, v184
	v_mul_f32_e32 v181, v149, v185
	s_nop 0
	v_add_f32_e32 v184, v181, v186
	v_add_f32_e32 v188, v180, v184
	v_fma_f32 v184, v42, s48, -v205
	v_exp_f32_e32 v185, v184
	v_fma_f32 v184, v43, s48, -v205
	v_exp_f32_e32 v184, v184
	v_fma_f32 v186, v44, s48, -v205
	v_exp_f32_e32 v187, v186
	v_fma_f32 v186, v45, s48, -v205
	v_mul_f32_e32 v184, v152, v184
	v_mul_f32_e32 v185, v153, v185
	v_exp_f32_e32 v186, v186
	v_add_f32_e32 v188, v185, v188
	v_add_f32_e32 v207, v184, v188
	v_fma_f32 v188, v46, s48, -v205
	v_exp_f32_e32 v189, v188
	v_fma_f32 v188, v47, s48, -v205
	v_exp_f32_e32 v188, v188
	v_mul_f32_e32 v186, v156, v186
	v_mul_f32_e32 v187, v157, v187
	v_mul_f32_e32 v188, v160, v188
	v_mul_f32_e32 v189, v161, v189
	v_add_f32_e32 v207, v187, v207
	v_add_f32_e32 v207, v186, v207
	v_add_f32_e32 v207, v189, v207
	v_add_f32_e32 v207, v188, v207

.LBB0_538:
	s_andn2_b64 vcc, exec, s[0:1]
	s_cbranch_vccnz .LBB0_540
	v_mul_f32_e32 v128, v134, v32
	v_mul_f32_e32 v176, v134, v36
	v_fmac_f32_e32 v128, v33, v135
	v_fmac_f32_e32 v176, v37, v135
	v_mul_f32_e32 v180, v134, v40
	v_mul_f32_e32 v182, v134, v44
	v_fmac_f32_e32 v128, v34, v136
	v_fmac_f32_e32 v176, v38, v136
	v_fmac_f32_e32 v180, v41, v135
	v_fmac_f32_e32 v182, v45, v135
	v_fmac_f32_e32 v128, v35, v137
	v_fmac_f32_e32 v176, v39, v137
	v_fmac_f32_e32 v180, v42, v136
	v_fmac_f32_e32 v182, v46, v136
	v_mul_f32_e32 v174, 0x3e38aa3b, v128
	v_mul_f32_e32 v175, 0x3e38aa3b, v176
	v_fmac_f32_e32 v180, v43, v137
	v_fmac_f32_e32 v182, v47, v137
	v_max3_f32 v174, v174, s53, v175
	v_mul_f32_e32 v175, 0x3e38aa3b, v180
	v_mul_f32_e32 v177, 0x3e38aa3b, v182
	v_max3_f32 v174, v174, v175, v177
	v_and_b32_e32 v177, 64, v191
	v_xor_b32_e32 v175, 32, v191
	v_add_u32_e32 v177, 64, v177
	v_cmp_lt_i32_e32 vcc, v175, v177
	s_nop 1
	v_cndmask_b32_e32 v175, v191, v175, vcc
	v_lshlrev_b32_e32 v175, 2, v175
	ds_bpermute_b32 v175, v175, v174
	s_waitcnt lgkmcnt(0)
	v_max3_f32 v205, v206, v174, v175
	v_fma_f32 v128, v128, s48, -v205
	v_exp_f32_e32 v175, v128
	v_fma_f32 v128, v176, s48, -v205
	v_exp_f32_e32 v174, v128
	v_fma_f32 v180, v180, s48, -v205
	v_exp_f32_e32 v181, v180
	v_fma_f32 v180, v182, s48, -v205
	v_exp_f32_e32 v180, v180
	v_sub_f32_e32 v128, v206, v205
	v_mul_f32_e32 v178, v146, v174
	v_mul_f32_e32 v179, v147, v175
	v_exp_f32_e32 v128, v128
	v_add_f32_e32 v183, 0, v179
	v_mul_f32_e32 v174, v134, v179
	v_mul_f32_e32 v175, v135, v179
	v_mul_f32_e32 v176, v136, v179
	v_mul_f32_e32 v177, v137, v179
	v_mul_f32_e32 v208, v134, v178
	v_mul_f32_e32 v209, v135, v178
	v_mul_f32_e32 v210, v136, v178
	v_mul_f32_e32 v211, v137, v178
	v_add_f32_e32 v184, v178, v183
	v_mul_f32_e32 v178, v144, v180
	v_mul_f32_e32 v179, v145, v181
	s_nop 0
	v_mul_f32_e32 v182, v134, v179
	v_mul_f32_e32 v183, v135, v179
	v_mul_f32_e32 v180, v136, v179
	v_mul_f32_e32 v181, v137, v179
	v_add_f32_e32 v188, v179, v184
	v_mul_f32_e32 v184, v134, v178
	v_mul_f32_e32 v185, v135, v178
	v_mul_f32_e32 v186, v136, v178
	v_mul_f32_e32 v187, v137, v178
	v_add_f32_e32 v207, v178, v188
	v_mov_b32_e32 v188, v187
	v_mov_b32_e32 v189, v186
	v_mov_b32_e32 v186, v185
	v_mov_b32_e32 v187, v184
	v_mov_b32_e32 v184, v181
	v_mov_b32_e32 v185, v180
	v_mov_b32_e32 v180, v183
	v_mov_b32_e32 v181, v182
	v_mov_b32_e32 v182, v211
	v_mov_b32_e32 v183, v210
	v_mov_b32_e32 v178, v209
	v_mov_b32_e32 v179, v208

.LBB0_541:
	v_mul_f32_e32 v32, v132, v32
	v_mul_f32_e32 v40, v132, v40
	v_fmac_f32_e32 v32, v33, v133
	v_fmac_f32_e32 v40, v41, v133
	v_fmac_f32_e32 v32, v34, v138
	v_fmac_f32_e32 v40, v42, v138
	v_fmac_f32_e32 v32, v35, v139
	v_fmac_f32_e32 v40, v43, v139
	v_fmac_f32_e32 v32, v36, v140
	v_fmac_f32_e32 v40, v44, v140
	v_fmac_f32_e32 v32, v37, v141
	v_fmac_f32_e32 v40, v45, v141
	v_and_b32_e32 v36, 64, v191
	v_fmac_f32_e32 v32, v38, v142
	v_fmac_f32_e32 v40, v46, v142
	v_xor_b32_e32 v35, 32, v191
	v_add_u32_e32 v36, 64, v36
	v_fmac_f32_e32 v32, v39, v143
	v_fmac_f32_e32 v40, v47, v143
	v_cmp_lt_i32_e32 vcc, v35, v36
	v_fmamk_f32 v32, v32, 0x3e38aa3b, v196
	v_fmamk_f32 v33, v40, 0x3e38aa3b, v196
	v_cndmask_b32_e32 v35, v191, v35, vcc
	v_max_f32_e32 v34, v32, v33
	v_lshlrev_b32_e32 v35, 2, v35
	ds_bpermute_b32 v35, v35, v34
	s_waitcnt lgkmcnt(0)
	v_max3_f32 v205, v206, v34, v35
	v_sub_f32_e32 v32, v32, v205
	v_sub_f32_e32 v33, v33, v205
	v_exp_f32_e32 v32, v32
	v_exp_f32_e32 v34, v33
	v_sub_f32_e32 v33, v206, v205
	v_exp_f32_e32 v128, v33
	v_mul_f32_e32 v40, v140, v32
	v_mul_f32_e32 v41, v141, v32
	v_mul_f32_e32 v36, v132, v34
	v_mul_f32_e32 v37, v133, v34
	v_mul_f32_e32 v38, v138, v34
	v_mul_f32_e32 v39, v139, v34
	v_mul_f32_e32 v42, v140, v34
	v_mul_f32_e32 v43, v141, v34
	v_mul_f32_e32 v44, v142, v32
	v_mul_f32_e32 v45, v143, v32
	v_mul_f32_e32 v46, v142, v34
	v_mul_f32_e32 v47, v143, v34
	v_mul_f32_e32 v174, v132, v32
	v_mul_f32_e32 v175, v133, v32
	v_mul_f32_e32 v176, v138, v32
	v_mul_f32_e32 v177, v139, v32
	v_add_f32_e32 v207, v32, v34
	v_mov_b32_e32 v179, v40
	v_mov_b32_e32 v178, v41
	v_mov_b32_e32 v183, v44
	v_mov_b32_e32 v182, v45
	v_mov_b32_e32 v181, v36
	v_mov_b32_e32 v180, v37
	v_mov_b32_e32 v185, v38
	v_mov_b32_e32 v184, v39
	v_mov_b32_e32 v187, v42
	v_mov_b32_e32 v186, v43
	v_mov_b32_e32 v189, v46
	v_mov_b32_e32 v188, v47
	v_cmp_eq_f32_e32 vcc, 1.0, v128
	s_cmp_eq_u64 vcc, exec
	s_cbranch_scc0 .LBB0_466
	s_branch .LBB0_467

.LBB0_545:
	s_andn2_b64 vcc, exec, s[42:43]
	s_cbranch_vccnz .LBB0_547
	v_max3_f32 v128, v208, s53, v209
	v_max3_f32 v128, v128, v210, v211
	v_max3_f32 v128, v128, v212, v213
	v_max3_f32 v128, v128, v214, v215
	v_and_b32_e32 v175, 64, v191
	v_max3_f32 v128, v128, v216, v217
	v_xor_b32_e32 v174, 32, v191
	v_add_u32_e32 v175, 64, v175
	v_max3_f32 v128, v128, v218, v219
	v_cmp_lt_i32_e32 vcc, v174, v175
	v_max3_f32 v128, v128, v220, v221
	v_max3_f32 v128, v128, v222, v223
	v_cndmask_b32_e32 v174, v191, v174, vcc
	v_lshlrev_b32_e32 v174, 2, v174
	ds_bpermute_b32 v174, v174, v128
	s_waitcnt lgkmcnt(0)
	v_max3_f32 v206, v205, v128, v174
	v_fma_f32 v128, v48, s48, -v206
	v_exp_f32_e32 v174, v128
	v_fma_f32 v128, v49, s48, -v206
	v_exp_f32_e32 v175, v128
	v_fma_f32 v177, v51, s48, -v206
	v_exp_f32_e32 v177, v177
	v_fma_f32 v178, v52, s48, -v206
	v_mul_f32_e32 v174, v150, v174
	v_mul_f32_e32 v175, v151, v175
	v_exp_f32_e32 v179, v178
	v_add_f32_e32 v176, 0, v174
	v_add_f32_e32 v180, v175, v176
	v_fma_f32 v176, v50, s48, -v206
	v_exp_f32_e32 v176, v176
	v_fma_f32 v178, v53, s48, -v206
	v_exp_f32_e32 v178, v178
	v_fma_f32 v182, v56, s48, -v206
	v_mul_f32_e32 v176, v154, v176
	v_mul_f32_e32 v177, v155, v177
	v_exp_f32_e32 v185, v182
	v_add_f32_e32 v180, v176, v180
	v_add_f32_e32 v180, v177, v180
	v_mul_f32_e32 v178, v158, v178
	v_mul_f32_e32 v179, v159, v179
	v_fma_f32 v182, v57, s48, -v206
	v_add_f32_e32 v180, v179, v180
	v_add_f32_e32 v186, v178, v180
	v_fma_f32 v180, v54, s48, -v206
	v_exp_f32_e32 v181, v180
	v_fma_f32 v180, v55, s48, -v206
	v_exp_f32_e32 v180, v180
	v_exp_f32_e32 v184, v182
	v_sub_f32_e32 v128, v205, v206
	v_exp_f32_e32 v128, v128
	v_mul_f32_e32 v182, v162, v180
	v_mul_f32_e32 v183, v163, v181
	s_nop 0
	v_add_f32_e32 v180, v183, v186
	v_add_f32_e32 v186, v182, v180
	v_mul_f32_e32 v180, v148, v184
	v_mul_f32_e32 v181, v149, v185
	s_nop 0
	v_add_f32_e32 v184, v181, v186
	v_add_f32_e32 v188, v180, v184
	v_fma_f32 v184, v58, s48, -v206
	v_exp_f32_e32 v185, v184
	v_fma_f32 v184, v59, s48, -v206
	v_exp_f32_e32 v184, v184
	v_fma_f32 v186, v60, s48, -v206
	v_exp_f32_e32 v187, v186
	v_fma_f32 v186, v61, s48, -v206
	v_mul_f32_e32 v184, v152, v184
	v_mul_f32_e32 v185, v153, v185
	v_exp_f32_e32 v186, v186
	v_add_f32_e32 v188, v185, v188
	v_add_f32_e32 v207, v184, v188
	v_fma_f32 v188, v62, s48, -v206
	v_exp_f32_e32 v189, v188
	v_fma_f32 v188, v63, s48, -v206
	v_exp_f32_e32 v188, v188
	v_mul_f32_e32 v186, v156, v186
	v_mul_f32_e32 v187, v157, v187
	v_mul_f32_e32 v188, v160, v188
	v_mul_f32_e32 v189, v161, v189
	v_add_f32_e32 v207, v187, v207
	v_add_f32_e32 v207, v186, v207
	v_add_f32_e32 v207, v189, v207
	v_add_f32_e32 v207, v188, v207

.LBB0_548:
	s_andn2_b64 vcc, exec, s[42:43]
	s_cbranch_vccnz .LBB0_550
	v_mul_f32_e32 v128, v134, v48
	v_mul_f32_e32 v176, v134, v52
	v_fmac_f32_e32 v128, v49, v135
	v_fmac_f32_e32 v176, v53, v135
	v_mul_f32_e32 v180, v134, v56
	v_mul_f32_e32 v182, v134, v60
	v_fmac_f32_e32 v128, v50, v136
	v_fmac_f32_e32 v176, v54, v136
	v_fmac_f32_e32 v180, v57, v135
	v_fmac_f32_e32 v182, v61, v135
	v_fmac_f32_e32 v128, v51, v137
	v_fmac_f32_e32 v176, v55, v137
	v_fmac_f32_e32 v180, v58, v136
	v_fmac_f32_e32 v182, v62, v136
	v_mul_f32_e32 v174, 0x3e38aa3b, v128
	v_mul_f32_e32 v175, 0x3e38aa3b, v176
	v_fmac_f32_e32 v180, v59, v137
	v_fmac_f32_e32 v182, v63, v137
	v_max3_f32 v174, v174, s53, v175
	v_mul_f32_e32 v175, 0x3e38aa3b, v180
	v_mul_f32_e32 v177, 0x3e38aa3b, v182
	v_max3_f32 v174, v174, v175, v177
	v_and_b32_e32 v177, 64, v191
	v_xor_b32_e32 v175, 32, v191
	v_add_u32_e32 v177, 64, v177
	v_cmp_lt_i32_e32 vcc, v175, v177
	s_nop 1
	v_cndmask_b32_e32 v175, v191, v175, vcc
	v_lshlrev_b32_e32 v175, 2, v175
	ds_bpermute_b32 v175, v175, v174
	s_waitcnt lgkmcnt(0)
	v_max3_f32 v206, v205, v174, v175
	v_fma_f32 v128, v128, s48, -v206
	v_exp_f32_e32 v175, v128
	v_fma_f32 v128, v176, s48, -v206
	v_exp_f32_e32 v174, v128
	v_fma_f32 v180, v180, s48, -v206
	v_exp_f32_e32 v181, v180
	v_fma_f32 v180, v182, s48, -v206
	v_exp_f32_e32 v180, v180
	v_sub_f32_e32 v128, v205, v206
	v_mul_f32_e32 v178, v146, v174
	v_mul_f32_e32 v179, v147, v175
	v_exp_f32_e32 v128, v128
	v_add_f32_e32 v183, 0, v179
	v_mul_f32_e32 v174, v134, v179
	v_mul_f32_e32 v175, v135, v179
	v_mul_f32_e32 v176, v136, v179
	v_mul_f32_e32 v177, v137, v179
	v_mul_f32_e32 v208, v134, v178
	v_mul_f32_e32 v209, v135, v178
	v_mul_f32_e32 v210, v136, v178
	v_mul_f32_e32 v211, v137, v178
	v_add_f32_e32 v184, v178, v183
	v_mul_f32_e32 v178, v144, v180
	v_mul_f32_e32 v179, v145, v181
	s_nop 0
	v_mul_f32_e32 v182, v134, v179
	v_mul_f32_e32 v183, v135, v179
	v_mul_f32_e32 v180, v136, v179
	v_mul_f32_e32 v181, v137, v179
	v_add_f32_e32 v188, v179, v184
	v_mul_f32_e32 v184, v134, v178
	v_mul_f32_e32 v185, v135, v178
	v_mul_f32_e32 v186, v136, v178
	v_mul_f32_e32 v187, v137, v178
	v_add_f32_e32 v207, v178, v188
	v_mov_b32_e32 v188, v187
	v_mov_b32_e32 v189, v186
	v_mov_b32_e32 v186, v185
	v_mov_b32_e32 v187, v184
	v_mov_b32_e32 v184, v181
	v_mov_b32_e32 v185, v180
	v_mov_b32_e32 v180, v183
	v_mov_b32_e32 v181, v182
	v_mov_b32_e32 v182, v211
	v_mov_b32_e32 v183, v210
	v_mov_b32_e32 v178, v209
	v_mov_b32_e32 v179, v208

.LBB0_551:
	v_mul_f32_e32 v48, v132, v48
	v_mul_f32_e32 v56, v132, v56
	v_fmac_f32_e32 v48, v49, v133
	v_fmac_f32_e32 v56, v57, v133
	v_fmac_f32_e32 v48, v50, v138
	v_fmac_f32_e32 v56, v58, v138
	v_fmac_f32_e32 v48, v51, v139
	v_fmac_f32_e32 v56, v59, v139
	v_fmac_f32_e32 v48, v52, v140
	v_fmac_f32_e32 v56, v60, v140
	v_fmac_f32_e32 v48, v53, v141
	v_fmac_f32_e32 v56, v61, v141
	v_and_b32_e32 v52, 64, v191
	v_fmac_f32_e32 v48, v54, v142
	v_fmac_f32_e32 v56, v62, v142
	v_xor_b32_e32 v51, 32, v191
	v_add_u32_e32 v52, 64, v52
	v_fmac_f32_e32 v48, v55, v143
	v_fmac_f32_e32 v56, v63, v143
	v_cmp_lt_i32_e32 vcc, v51, v52
	v_fmamk_f32 v48, v48, 0x3e38aa3b, v196
	v_fmamk_f32 v49, v56, 0x3e38aa3b, v196
	v_cndmask_b32_e32 v51, v191, v51, vcc
	v_max_f32_e32 v50, v48, v49
	v_lshlrev_b32_e32 v51, 2, v51
	ds_bpermute_b32 v51, v51, v50
	s_waitcnt lgkmcnt(0)
	v_max3_f32 v206, v205, v50, v51
	v_sub_f32_e32 v48, v48, v206
	v_sub_f32_e32 v49, v49, v206
	v_exp_f32_e32 v48, v48
	v_exp_f32_e32 v50, v49
	v_sub_f32_e32 v49, v205, v206
	v_exp_f32_e32 v128, v49
	v_mul_f32_e32 v56, v140, v48
	v_mul_f32_e32 v57, v141, v48
	v_mul_f32_e32 v52, v132, v50
	v_mul_f32_e32 v53, v133, v50
	v_mul_f32_e32 v54, v138, v50
	v_mul_f32_e32 v55, v139, v50
	v_mul_f32_e32 v58, v140, v50
	v_mul_f32_e32 v59, v141, v50
	v_mul_f32_e32 v60, v142, v48
	v_mul_f32_e32 v61, v143, v48
	v_mul_f32_e32 v62, v142, v50
	v_mul_f32_e32 v63, v143, v50
	v_mul_f32_e32 v174, v132, v48
	v_mul_f32_e32 v175, v133, v48
	v_mul_f32_e32 v176, v138, v48
	v_mul_f32_e32 v177, v139, v48
	v_add_f32_e32 v207, v48, v50
	v_mov_b32_e32 v179, v56
	v_mov_b32_e32 v178, v57
	v_mov_b32_e32 v183, v60
	v_mov_b32_e32 v182, v61
	v_mov_b32_e32 v181, v52
	v_mov_b32_e32 v180, v53
	v_mov_b32_e32 v185, v54
	v_mov_b32_e32 v184, v55
	v_mov_b32_e32 v187, v58
	v_mov_b32_e32 v186, v59
	v_mov_b32_e32 v189, v62
	v_mov_b32_e32 v188, v63
	v_cmp_eq_f32_e32 vcc, 1.0, v128
	s_cmp_eq_u64 vcc, exec
	s_cbranch_scc0 .LBB0_475
	s_branch .LBB0_476

.LBB0_555:
	s_andn2_b64 vcc, exec, s[0:1]
	s_cbranch_vccnz .LBB0_557
	v_max3_f32 v112, v128, s53, v176
	v_max3_f32 v112, v112, v177, v178
	v_max3_f32 v112, v112, v179, v180
	v_max3_f32 v112, v112, v181, v182
	v_and_b32_e32 v114, 64, v191
	v_max3_f32 v112, v112, v183, v184
	v_xor_b32_e32 v113, 32, v191
	v_add_u32_e32 v114, 64, v114
	v_max3_f32 v112, v112, v185, v186
	v_cmp_lt_i32_e32 vcc, v113, v114
	v_max3_f32 v112, v112, v187, v188
	v_max3_f32 v112, v112, v189, v207
	v_cndmask_b32_e32 v113, v191, v113, vcc
	v_lshlrev_b32_e32 v113, 2, v113
	ds_bpermute_b32 v113, v113, v112
	s_waitcnt lgkmcnt(0)
	v_max3_f32 v205, v206, v112, v113
	v_fma_f32 v112, v32, s48, -v205
	v_fma_f32 v113, v33, s48, -v205
	v_exp_f32_e32 v112, v112
	v_exp_f32_e32 v113, v113
	v_fma_f32 v115, v35, s48, -v205
	v_exp_f32_e32 v115, v115
	v_fma_f32 v116, v36, s48, -v205
	v_mul_f32_e32 v112, v150, v112
	v_mul_f32_e32 v113, v151, v113
	v_exp_f32_e32 v117, v116
	v_add_f32_e32 v114, 0, v112
	v_add_f32_e32 v118, v113, v114
	v_fma_f32 v114, v34, s48, -v205
	v_exp_f32_e32 v114, v114
	v_fma_f32 v116, v37, s48, -v205
	v_exp_f32_e32 v116, v116
	v_fma_f32 v120, v40, s48, -v205
	v_mul_f32_e32 v114, v154, v114
	v_mul_f32_e32 v115, v155, v115
	v_exp_f32_e32 v123, v120
	v_add_f32_e32 v118, v114, v118
	v_add_f32_e32 v118, v115, v118
	v_mul_f32_e32 v116, v158, v116
	v_mul_f32_e32 v117, v159, v117
	v_fma_f32 v120, v41, s48, -v205
	v_add_f32_e32 v118, v117, v118
	v_add_f32_e32 v124, v116, v118
	v_fma_f32 v118, v38, s48, -v205
	v_exp_f32_e32 v119, v118
	v_fma_f32 v118, v39, s48, -v205
	v_exp_f32_e32 v118, v118
	v_exp_f32_e32 v122, v120
	v_fma_f32 v128, v46, s48, -v205
	v_exp_f32_e32 v175, v128
	v_mul_f32_e32 v120, v162, v118
	v_mul_f32_e32 v121, v163, v119
	v_fma_f32 v128, v47, s48, -v205
	v_add_f32_e32 v118, v121, v124
	v_add_f32_e32 v124, v120, v118
	v_mul_f32_e32 v118, v148, v122
	v_mul_f32_e32 v119, v149, v123
	v_exp_f32_e32 v174, v128
	v_add_f32_e32 v122, v119, v124
	v_add_f32_e32 v127, v118, v122
	v_fma_f32 v122, v42, s48, -v205
	v_exp_f32_e32 v123, v122
	v_fma_f32 v122, v43, s48, -v205
	v_exp_f32_e32 v122, v122
	v_fma_f32 v124, v44, s48, -v205
	v_exp_f32_e32 v125, v124
	v_fma_f32 v124, v45, s48, -v205
	v_exp_f32_e32 v124, v124
	v_mul_f32_e32 v122, v152, v122
	v_mul_f32_e32 v123, v153, v123
	v_sub_f32_e32 v126, v206, v205
	v_add_f32_e32 v127, v123, v127
	v_add_f32_e32 v127, v122, v127
	v_mul_f32_e32 v124, v156, v124
	v_mul_f32_e32 v125, v157, v125
	v_exp_f32_e32 v126, v126
	v_add_f32_e32 v127, v125, v127
	v_add_f32_e32 v127, v124, v127
	v_mul_f32_e32 v174, v160, v174
	v_mul_f32_e32 v175, v161, v175
	s_nop 0
	v_add_f32_e32 v127, v175, v127
	v_add_f32_e32 v127, v174, v127

.LBB0_558:
	s_andn2_b64 vcc, exec, s[0:1]
	s_cbranch_vccnz .LBB0_560
	v_mul_f32_e32 v112, v134, v32
	v_mul_f32_e32 v114, v134, v36
	v_fmac_f32_e32 v112, v33, v135
	v_fmac_f32_e32 v114, v37, v135
	v_mul_f32_e32 v118, v134, v40
	v_mul_f32_e32 v120, v134, v44
	v_fmac_f32_e32 v112, v34, v136
	v_fmac_f32_e32 v114, v38, v136
	v_fmac_f32_e32 v118, v41, v135
	v_fmac_f32_e32 v120, v45, v135
	v_fmac_f32_e32 v112, v35, v137
	v_fmac_f32_e32 v114, v39, v137
	v_fmac_f32_e32 v118, v42, v136
	v_fmac_f32_e32 v120, v46, v136
	v_mul_f32_e32 v113, 0x3e38aa3b, v112
	v_mul_f32_e32 v115, 0x3e38aa3b, v114
	v_fmac_f32_e32 v118, v43, v137
	v_fmac_f32_e32 v120, v47, v137
	v_max3_f32 v113, v113, s53, v115
	v_mul_f32_e32 v115, 0x3e38aa3b, v118
	v_mul_f32_e32 v116, 0x3e38aa3b, v120
	v_max3_f32 v113, v113, v115, v116
	v_and_b32_e32 v116, 64, v191
	v_xor_b32_e32 v115, 32, v191
	v_add_u32_e32 v116, 64, v116
	v_cmp_lt_i32_e32 vcc, v115, v116
	s_nop 1
	v_cndmask_b32_e32 v115, v191, v115, vcc
	v_lshlrev_b32_e32 v115, 2, v115
	ds_bpermute_b32 v115, v115, v113
	s_waitcnt lgkmcnt(0)
	v_max3_f32 v205, v206, v113, v115
	v_fma_f32 v112, v112, s48, -v205
	v_exp_f32_e32 v113, v112
	v_fma_f32 v112, v114, s48, -v205
	v_exp_f32_e32 v112, v112
	v_fma_f32 v118, v118, s48, -v205
	v_exp_f32_e32 v119, v118
	v_fma_f32 v118, v120, s48, -v205
	v_exp_f32_e32 v118, v118
	v_sub_f32_e32 v126, v206, v205
	v_mul_f32_e32 v116, v146, v112
	v_mul_f32_e32 v117, v147, v113
	v_exp_f32_e32 v126, v126
	v_add_f32_e32 v121, 0, v117
	v_mul_f32_e32 v112, v134, v117
	v_mul_f32_e32 v113, v135, v117
	v_mul_f32_e32 v114, v136, v117
	v_mul_f32_e32 v115, v137, v117
	v_mul_f32_e32 v176, v134, v116
	v_mul_f32_e32 v177, v135, v116
	v_mul_f32_e32 v178, v136, v116
	v_mul_f32_e32 v179, v137, v116
	v_add_f32_e32 v122, v116, v121
	v_mul_f32_e32 v116, v144, v118
	v_mul_f32_e32 v117, v145, v119
	s_nop 0
	v_mul_f32_e32 v120, v134, v117
	v_mul_f32_e32 v121, v135, v117
	v_mul_f32_e32 v118, v136, v117
	v_mul_f32_e32 v119, v137, v117
	v_add_f32_e32 v127, v117, v122
	v_mul_f32_e32 v122, v134, v116
	v_mul_f32_e32 v123, v135, v116
	v_mul_f32_e32 v124, v136, v116
	v_mul_f32_e32 v125, v137, v116
	v_add_f32_e32 v127, v116, v127
	v_mov_b32_e32 v174, v125
	v_mov_b32_e32 v175, v124
	v_mov_b32_e32 v124, v123
	v_mov_b32_e32 v125, v122
	v_mov_b32_e32 v122, v119
	v_mov_b32_e32 v123, v118
	v_mov_b32_e32 v118, v121
	v_mov_b32_e32 v119, v120
	v_mov_b32_e32 v120, v179
	v_mov_b32_e32 v121, v178
	v_mov_b32_e32 v116, v177
	v_mov_b32_e32 v117, v176

.LBB0_561:
	v_mul_f32_e32 v32, v132, v32
	v_mul_f32_e32 v40, v132, v40
	v_fmac_f32_e32 v32, v33, v133
	v_fmac_f32_e32 v40, v41, v133
	v_fmac_f32_e32 v32, v34, v138
	v_fmac_f32_e32 v40, v42, v138
	v_fmac_f32_e32 v32, v35, v139
	v_fmac_f32_e32 v40, v43, v139
	v_fmac_f32_e32 v32, v36, v140
	v_fmac_f32_e32 v40, v44, v140
	v_fmac_f32_e32 v32, v37, v141
	v_fmac_f32_e32 v40, v45, v141
	v_and_b32_e32 v36, 64, v191
	v_fmac_f32_e32 v32, v38, v142
	v_fmac_f32_e32 v40, v46, v142
	v_xor_b32_e32 v35, 32, v191
	v_add_u32_e32 v36, 64, v36
	v_fmac_f32_e32 v32, v39, v143
	v_fmac_f32_e32 v40, v47, v143
	v_cmp_lt_i32_e32 vcc, v35, v36
	v_fmamk_f32 v32, v32, 0x3e38aa3b, v196
	v_fmamk_f32 v33, v40, 0x3e38aa3b, v196
	v_cndmask_b32_e32 v35, v191, v35, vcc
	v_max_f32_e32 v34, v32, v33
	v_lshlrev_b32_e32 v35, 2, v35
	ds_bpermute_b32 v35, v35, v34
	s_waitcnt lgkmcnt(0)
	v_max3_f32 v205, v206, v34, v35
	v_sub_f32_e32 v32, v32, v205
	v_sub_f32_e32 v33, v33, v205
	v_exp_f32_e32 v32, v32
	v_exp_f32_e32 v34, v33
	v_sub_f32_e32 v33, v206, v205
	v_exp_f32_e32 v126, v33
	v_mul_f32_e32 v40, v140, v32
	v_mul_f32_e32 v41, v141, v32
	v_mul_f32_e32 v36, v132, v34
	v_mul_f32_e32 v37, v133, v34
	v_mul_f32_e32 v38, v138, v34
	v_mul_f32_e32 v39, v139, v34
	v_mul_f32_e32 v42, v140, v34
	v_mul_f32_e32 v43, v141, v34
	v_mul_f32_e32 v44, v142, v32
	v_mul_f32_e32 v45, v143, v32
	v_mul_f32_e32 v46, v142, v34
	v_mul_f32_e32 v47, v143, v34
	v_mul_f32_e32 v112, v132, v32
	v_mul_f32_e32 v113, v133, v32
	v_mul_f32_e32 v114, v138, v32
	v_mul_f32_e32 v115, v139, v32
	v_add_f32_e32 v127, v32, v34
	v_mov_b32_e32 v117, v40
	v_mov_b32_e32 v116, v41
	v_mov_b32_e32 v121, v44
	v_mov_b32_e32 v120, v45
	v_mov_b32_e32 v119, v36
	v_mov_b32_e32 v118, v37
	v_mov_b32_e32 v123, v38
	v_mov_b32_e32 v122, v39
	v_mov_b32_e32 v125, v42
	v_mov_b32_e32 v124, v43
	v_mov_b32_e32 v175, v46
	v_mov_b32_e32 v174, v47
	v_cmp_eq_f32_e32 vcc, 1.0, v126
	s_cmp_eq_u64 vcc, exec
	s_cbranch_scc0 .LBB0_482
	s_branch .LBB0_483
